# all per-phase s_setprio flips of the GEMM K-loops deleted (A/B of the template's priority toggles)
# speedup vs baseline: 1.0182x; 1.0182x over previous
; DI int get_tid() { int t = threadIdx.x; asm volatile("" : "+v"(t)); return t; }
; #define LAUNDER(Q) Params Q = P; asm volatile("" : "+s"(Q.ws), "+s"(Q.out), "+s"(Q.x), "+s"(Q.rel), "+s"(Q.g_sub), "+s"(Q.sinks))
; DI void phase_w(const Params& P, char* lds) {
;     const int tid = get_tid();
;     const int half = tid >> 8, t = tid & 255;
;     constexpr int NI_IN = 2 * 16 * 110, NI_OUT = 2 * 32 * 16, NI_MOD = 96;
;     u16* win_t = (u16*)(P.ws + WS_WIN);
;     u16* wout_t = (u16*)(P.ws + WS_WOUT);
;     for (int pr = blockIdx.x; pr < (NI_IN + NI_OUT + NI_MOD) / 2; pr += gridDim.x) {
;         const int it = 2 * pr + half;
;         if (it < NI_IN + NI_OUT) {
;             const float* W; u16* WT; int K, N, kt, nt;
;             if (it < NI_IN) { int l = it / 1760, r = it % 1760; K = 1024; N = 7040; W = P.w_in + (size_t)l * 1024 * 7040; WT = win_t + (size_t)l * 7168 * 1024; kt = r / 110; nt = r % 110; }
;             else { int r0 = it - NI_IN; int l = r0 / 512, r = r0 % 512; K = 2048; N = 1024; W = P.w_out + (size_t)l * 2048 * 1024; WT = wout_t + (size_t)l * 1024 * 2048; kt = r / 16; nt = r % 16; }
;             float* tile = (float*)(lds + half * 16896);
;             const int ty = t >> 4, tx = t & 15;
; __global__ void __launch_bounds__(512, 1) mega(Params P) {
;     ...
;     if (__builtin_amdgcn_readfirstlane(threadIdx.x) >= 256) __builtin_amdgcn_s_setprio(1);
;     { LAUNDER(Q); phase_w(Q, lds); }
.LBB0_5:
	s_or_b64 exec, exec, s[4:5]
	v_readfirstlane_b32 s3, v174
	s_cmpk_lt_i32 s3, 0x100
	s_cbranch_scc1 .LBB0_7
.LBB0_7:
	s_load_dwordx8 s[12:19], s[0:1], 0x0
	s_load_dwordx4 s[8:11], s[0:1], 0x68
	s_load_dwordx2 s[98:99], s[0:1], 0x78
	s_load_dwordx8 s[36:43], s[0:1], 0x48
	s_mov_b64 s[28:29], s[60:61]
	s_waitcnt lgkmcnt(0)
	s_mov_b64 s[4:5], s[12:13]
	v_writelane_b32 v237, s8, 0
	s_mov_b64 s[6:7], s[10:11]
	v_mov_b32_e32 v2, v174
	v_writelane_b32 v237, s9, 1
	v_writelane_b32 v237, s10, 2
	v_writelane_b32 v237, s11, 3
	v_writelane_b32 v237, s12, 4
	s_mov_b64 s[8:9], s[98:99]
	s_mov_b64 s[30:31], s[16:17]
	v_writelane_b32 v237, s13, 5
	v_writelane_b32 v237, s14, 6
	v_writelane_b32 v237, s15, 7
	v_writelane_b32 v237, s16, 8
	v_writelane_b32 v237, s17, 9
	v_writelane_b32 v237, s18, 10
	v_writelane_b32 v237, s19, 11
	v_writelane_b32 v237, s36, 12
	s_mov_b64 s[10:11], s[36:37]
	s_add_u32 s34, s28, 0x100000
	v_writelane_b32 v237, s37, 13
	v_writelane_b32 v237, s38, 14
	v_writelane_b32 v237, s39, 15
	v_writelane_b32 v237, s40, 16
	v_writelane_b32 v237, s41, 17
	s_addc_u32 s35, s29, 0
	v_writelane_b32 v237, s42, 18
	s_cmpk_gt_i32 s33, 0x90f
	v_writelane_b32 v237, s43, 19
	s_cbranch_scc1 .LBB0_34
	v_lshlrev_b32_e32 v10, 4, v2
	v_ashrrev_i32_e32 v1, 8, v2
	s_movk_i32 s3, 0x1000
	v_and_b32_e32 v20, 63, v2
	v_bfe_u32 v21, v2, 6, 2
	v_and_b32_e32 v10, 48, v10
	v_and_b32_e32 v3, 0xff, v2
	v_lshl_add_u32 v4, v1, 12, 0
	v_cmp_gt_i32_e64 s[12:13], s3, v2
	v_lshlrev_b32_e32 v5, 2, v20
	v_lshlrev_b32_e32 v8, 10, v21
	s_movk_i32 s3, 0x3200
	v_lshlrev_b32_e32 v25, 2, v2
	v_mul_u32_u24_e32 v13, 0x41, v10
	v_add3_u32 v22, v4, v8, v5
	v_lshl_add_u32 v23, v3, 2, v4
	v_mad_i32_i24 v3, v1, s3, v4
	v_and_b32_e32 v4, 60, v25
	v_and_b32_e32 v11, 0xfc, v2
	v_lshlrev_b32_e32 v13, 2, v13
	v_lshl_add_u32 v9, v4, 2, v3
	v_add3_u32 v30, v3, v11, v13
	v_add3_u32 v31, v3, v13, v11
	v_max_i32_e32 v3, 0xe00, v2
	v_sub_u32_e32 v3, v3, v2
	s_load_dwordx4 s[20:23], s[0:1], 0x20
	s_load_dwordx2 s[36:37], s[0:1], 0x30
	v_add_u32_e32 v3, 0x1ff, v3
	v_lshrrev_b32_e32 v11, 9, v3
	s_add_u32 s38, s28, 0x1d00000
	v_add_u32_e32 v13, 1, v11
	v_add_u32_e32 v11, -1, v11
	s_addc_u32 s39, s29, 0
	v_bfe_u32 v24, v2, 4, 4
	s_movk_i32 s3, 0x1ff
	v_lshrrev_b32_e32 v14, 1, v11
	s_waitcnt lgkmcnt(0)
	v_mov_b32_e32 v6, s22
	v_mov_b32_e32 v7, s23
	v_mul_u32_u24_e32 v12, 0x104, v24
	s_add_u32 s22, s28, 0x1000
	v_add_u32_e32 v14, 1, v14
	v_cmp_lt_u32_e64 s[4:5], s3, v3
	v_and_b32_e32 v15, 0xfffffe, v13
	v_cmp_lt_u32_e64 s[6:7], 1, v11
	v_and_b32_e32 v11, 2, v11
	s_mov_b32 s3, 0x300000
	v_mov_b32_e32 v5, 0
	v_bfe_u32 v26, v2, 2, 6
	v_or_b32_e32 v27, 16, v24
	v_or_b32_e32 v28, 32, v24
	v_or_b32_e32 v29, 48, v24
	s_addc_u32 s23, s29, 0
	v_lshl_add_u32 v32, v15, 9, v2
	v_add_u32_e32 v3, 0x200, v2
	v_and_b32_e32 v33, -2, v14
	v_cmp_eq_u32_e64 s[8:9], 0, v11
	v_cmp_ne_u32_e64 s[10:11], v13, v15
	v_add_u32_e32 v34, 0, v25
	v_mad_u64_u32 v[6:7], s[14:15], v21, s3, v[6:7]
	v_add_u32_e32 v35, 0, v8
	s_movk_i32 s3, 0x11bf
	s_mov_b32 s44, 0xbfb8aa3b
	s_mov_b32 s45, 0x42ce8ed0
	s_mov_b32 s46, 0xc2b17218
	s_mov_b64 s[40:41], 0x800
	s_movk_i32 s47, 0xdff
	s_mov_b32 s48, 0xaaaaaaab
	s_mov_b32 s49, 0xc00000
	s_movk_i32 s50, 0x3000
	s_movk_i32 s51, 0x6000
	s_mov_b32 s52, 0x9000
	s_mov_b32 s53, 0xc000
	s_mov_b32 s54, 0xf000
	s_mov_b32 s55, 0x12000
	s_mov_b32 s56, 0x15000
	s_movk_i32 s57, 0xc00
	s_movk_i32 s58, 0xdbf
	s_mov_b32 s59, 0x94f2095
	s_mov_b32 s88, 0x1b80000
	s_mov_b32 s89, 0xe00000
	v_lshlrev_b32_e32 v8, 2, v4
	v_add_u32_e32 v36, v9, v12
	v_lshlrev_b32_e32 v10, 1, v10
	v_mov_b32_e32 v37, 0x7f800000
	s_mov_b32 s66, s33
	s_branch .LBB0_11

; #define PG8_STAGE(bufoff, gbase, voff) do { _Pragma("unroll") for (int _i = 0; _i < 2; ++_i) \
;         __builtin_amdgcn_global_load_lds((const unsigned*)((const char*)(gbase) + (voff)[_i]), (LAS unsigned*)(lds + (bufoff) + ldsw + _i * 8192), 16, 0, 0); } while (0)
; #define PG8_LDA(dst, b, h) do { _Pragma("unroll") for (int m = 0; m < 4; ++m) _Pragma("unroll") for (int k = 0; k < 2; ++k) dst[m][k] = *(const LAS bf16x8*)(lds + PG8_SA(b, h) + aoff + m * 2048 + k * 1024); } while (0)
; #define PG8_WAIT_V(n) asm volatile("s_waitcnt vmcnt(" #n ")" ::: "memory")
; template <bool REMAP>
; DI void gemm_phase(LAS unsigned char* lds, const u16* A, int lda, const u16* Bt, int K, u16* O, int ldc, int nunits) {
;     ...
;     const char* cA = (const char*)A + (size_t)cur.pm * tstepA; const char* cB = (const char*)Bt + (size_t)cur.pn * tstepB;
;     PG8_STAGE(PG8_SB(0, 0), cB, voffB); PG8_STAGE(PG8_SA(0, 0), cA + akb(0), voffA); PG8_STAGE(PG8_SB(0, 1), cB + hstepB, voffB); PG8_STAGE(PG8_SA(0, 1), cA + akb(0) + hstepA, voffA);
;     if (wr == 1) PG8_BAR;
;     PG8_WAIT_V(4); PG8_BAR;
;     PG8_STAGE(PG8_SB(1, 0), cB + kstep, voffB); PG8_STAGE(PG8_SA(1, 0), cA + akb(1), voffA); PG8_STAGE(PG8_SB(1, 1), cB + hstepB + kstep, voffB);
;     PG8_WAIT_V(6); PG8_BAR;
;     for (;;) {
;         const bool has_next = next_unit(ui + 1, nunits, nxt);
;         const char* nA = has_next ? (const char*)A + (size_t)nxt.pm * tstepA : cA; const char* nB = has_next ? (const char*)Bt + (size_t)nxt.pn * tstepB : cB;
;         for (int t = 0; t < nt; t += 2) {
;             const bool last = (t == nt - 2);
;             const char* a1 = cA + akb(t + 1);
;             const char* a2 = last ? nA + akb(0) : cA + akb(t + 2); const char* b2 = last ? nB : cB + (size_t)(t + 2) * kstep;
;             const char* a3 = last ? nA + akb(1) : cA + akb(t + 3); const char* b3 = b2 + kstep;
;             PG8_LDB(B0, 0, 0); PG8_SCHED; PG8_LDA(At, 0, 0); PG8_STAGE(PG8_SA(1, 1), a1 + hstepA, voffA);
;             PG8_WAIT_L(8); PG8_BAR; PG8_WAIT_L(0); PG8_MMA(0, 0, At, B0); PG8_BAR; PG8_SCHED;
;             PG8_LDB(B1, 0, 1); PG8_STAGE(PG8_SB(0, 0), b2, voffB);
;             PG8_BAR; PG8_WAIT_L(0); PG8_MMA(0, 1, At, B1); PG8_BAR;
;             PG8_LDA(At, 0, 1); PG8_STAGE(PG8_SA(0, 0), a2, voffA);
;             PG8_BAR; PG8_WAIT_L(0); PG8_MMA(1, 0, At, B0); PG8_BAR; PG8_SCHED;
.LBB0_136:
	s_ashr_i32 s5, s4, 31
	s_lshl_b64 s[12:13], s[4:5], 19
	s_add_u32 s12, s3, s12
	s_addc_u32 s13, s24, s13
	s_and_b64 s[14:15], s[22:23], exec
	s_cselect_b32 s5, s13, s11
	s_cselect_b32 s46, s12, s10
	s_ashr_i32 s7, s6, 31
	s_lshl_b64 s[14:15], s[6:7], 19
	s_add_u32 s14, s16, s14
	s_addc_u32 s15, s25, s15
	s_and_b64 s[22:23], s[22:23], exec
	s_cselect_b32 s7, s15, s21
	s_cselect_b32 s47, s14, s20
	s_add_u32 s49, s46, 0x80
	s_addc_u32 s50, s5, 0
	s_add_u32 s51, s20, 0x100
	s_addc_u32 s54, s21, 0
	s_add_u32 s22, s10, 0x40080
	s_addc_u32 s23, s11, 0
	s_mov_b32 s55, -2
	s_mov_b64 s[20:21], 0
	v_lshl_add_u64 v[140:141], s[22:23], 0, v[136:137]
	v_lshl_add_u64 v[142:143], s[22:23], 0, v[138:139]
	s_add_u32 s22, s10, s20
	s_addc_u32 s23, s11, s21
	s_add_u32 s30, s22, 0x100
	s_addc_u32 s31, s23, 0
	s_add_u32 s56, s51, s20
	s_addc_u32 s57, s54, s21
	s_add_u32 s22, s22, 0x180
	s_addc_u32 s23, s23, 0
	s_add_i32 s58, 0, 0x10000
	v_add_u32_e32 v160, s58, v145
	ds_read_b128 v[148:151], v160
	ds_read_b128 v[152:155], v160 offset:1024
	ds_read_b128 v[156:159], v160 offset:2048
	ds_read_b128 v[160:163], v160 offset:3072
	s_cmpk_eq_i32 s20, 0x700
	s_cselect_b32 s29, s50, s23
	s_cselect_b32 s28, s49, s22
	s_cselect_b32 s23, s7, s57
	s_cselect_b32 s22, s47, s56
	s_cselect_b32 s31, s5, s31
	s_cselect_b32 s30, s46, s30
	v_lshl_add_u64 v[172:173], v[142:143], 0, s[20:21]
	s_add_i32 m0, s27, 0xc000
	ds_read_b128 v[164:167], v147
	ds_read_b128 v[168:171], v147 offset:1024
	ds_read_b128 v[192:195], v147 offset:2048
	ds_read_b128 v[196:199], v147 offset:3072
	ds_read_b128 v[200:203], v147 offset:4096
	ds_read_b128 v[204:207], v147 offset:5120
	ds_read_b128 v[208:211], v147 offset:6144
	ds_read_b128 v[212:215], v147 offset:7168
	global_load_lds_dwordx4 v[172:173], off
	v_lshl_add_u64 v[172:173], v[140:141], 0, s[20:21]
	s_add_i32 m0, s27, 0xe000
	s_nop 0
	global_load_lds_dwordx4 v[172:173], off
	s_waitcnt lgkmcnt(8)
	s_barrier
	s_waitcnt lgkmcnt(0)
	s_waitcnt lgkmcnt(0)
	v_mfma_f32_16x16x32_bf16 v[126:129], v[148:151], v[164:167], 0
	v_mfma_f32_16x16x32_bf16 v[122:125], v[156:159], v[164:167], 0
	v_mfma_f32_16x16x32_bf16 v[118:121], v[148:151], v[192:195], 0
	v_mfma_f32_16x16x32_bf16 v[114:117], v[156:159], v[192:195], 0
	v_mfma_f32_16x16x32_bf16 v[102:105], v[148:151], v[200:203], 0
	v_mfma_f32_16x16x32_bf16 v[98:101], v[156:159], v[200:203], 0
	v_mfma_f32_16x16x32_bf16 v[86:89], v[148:151], v[208:211], 0
	v_mfma_f32_16x16x32_bf16 v[82:85], v[156:159], v[208:211], 0
	v_mfma_f32_16x16x32_bf16 v[126:129], v[152:155], v[168:171], v[126:129]
	v_mfma_f32_16x16x32_bf16 v[122:125], v[160:163], v[168:171], v[122:125]
	v_mfma_f32_16x16x32_bf16 v[118:121], v[152:155], v[196:199], v[118:121]
	v_mfma_f32_16x16x32_bf16 v[114:117], v[160:163], v[196:199], v[114:117]
	v_mfma_f32_16x16x32_bf16 v[102:105], v[152:155], v[204:207], v[102:105]
	v_mfma_f32_16x16x32_bf16 v[98:101], v[160:163], v[204:207], v[98:101]
	v_mfma_f32_16x16x32_bf16 v[86:89], v[152:155], v[212:215], v[86:89]
	v_mfma_f32_16x16x32_bf16 v[82:85], v[160:163], v[212:215], v[82:85]
	s_barrier
	s_add_i32 s59, 0, 0x14000
	v_add_u32_e32 v172, s59, v145
	s_add_i32 s56, s58, s26
	ds_read_b128 v[216:219], v172
	ds_read_b128 v[220:223], v172 offset:1024
	ds_read_b128 v[224:227], v172 offset:2048
	ds_read_b128 v[228:231], v172 offset:3072
	v_lshl_add_u64 v[172:173], s[22:23], 0, v[0:1]
	s_mov_b32 m0, s56
	v_lshl_add_u64 v[232:233], s[22:23], 0, v[130:131]
	global_load_lds_dwordx4 v[172:173], off
	s_add_i32 m0, s56, 0x2000
	s_nop 0
	global_load_lds_dwordx4 v[232:233], off
	s_barrier
	s_waitcnt lgkmcnt(0)
	s_waitcnt lgkmcnt(0)
	v_mfma_f32_16x16x32_bf16 v[110:113], v[216:219], v[164:167], 0
	v_mfma_f32_16x16x32_bf16 v[106:109], v[224:227], v[164:167], 0
	v_mfma_f32_16x16x32_bf16 v[94:97], v[216:219], v[192:195], 0
	v_mfma_f32_16x16x32_bf16 v[90:93], v[224:227], v[192:195], 0
	v_mfma_f32_16x16x32_bf16 v[78:81], v[216:219], v[200:203], 0
	v_mfma_f32_16x16x32_bf16 v[74:77], v[224:227], v[200:203], 0
	v_mfma_f32_16x16x32_bf16 v[70:73], v[216:219], v[208:211], 0
	v_mfma_f32_16x16x32_bf16 v[66:69], v[224:227], v[208:211], 0
	v_mfma_f32_16x16x32_bf16 v[110:113], v[220:223], v[168:171], v[110:113]
	v_mfma_f32_16x16x32_bf16 v[106:109], v[228:231], v[168:171], v[106:109]
	v_mfma_f32_16x16x32_bf16 v[94:97], v[220:223], v[196:199], v[94:97]
	v_mfma_f32_16x16x32_bf16 v[90:93], v[228:231], v[196:199], v[90:93]
	v_mfma_f32_16x16x32_bf16 v[78:81], v[220:223], v[204:207], v[78:81]
	v_mfma_f32_16x16x32_bf16 v[74:77], v[228:231], v[204:207], v[74:77]
	v_mfma_f32_16x16x32_bf16 v[70:73], v[220:223], v[212:215], v[70:73]
	v_mfma_f32_16x16x32_bf16 v[66:69], v[228:231], v[212:215], v[66:69]
	s_mov_b32 m0, s27
	v_lshl_add_u64 v[234:235], s[30:31], 0, v[134:135]
	s_barrier
	ds_read_b128 v[164:167], v147 offset:16384
	ds_read_b128 v[168:171], v147 offset:17408
	ds_read_b128 v[192:195], v147 offset:18432
	ds_read_b128 v[196:199], v147 offset:19456
	ds_read_b128 v[200:203], v147 offset:20480
	ds_read_b128 v[204:207], v147 offset:21504
	ds_read_b128 v[208:211], v147 offset:22528
	ds_read_b128 v[212:215], v147 offset:23552
	global_load_lds_dwordx4 v[234:235], off
	v_lshl_add_u64 v[234:235], s[30:31], 0, v[132:133]
	s_mov_b32 m0, s34
	s_nop 0
	global_load_lds_dwordx4 v[234:235], off
	s_barrier
; #define PG8_STAGE(bufoff, gbase, voff) do { _Pragma("unroll") for (int _i = 0; _i < 2; ++_i) \
;         __builtin_amdgcn_global_load_lds((const unsigned*)((const char*)(gbase) + (voff)[_i]), (LAS unsigned*)(lds + (bufoff) + ldsw + _i * 8192), 16, 0, 0); } while (0)
; #define PG8_LDA(dst, b, h) do { _Pragma("unroll") for (int m = 0; m < 4; ++m) _Pragma("unroll") for (int k = 0; k < 2; ++k) dst[m][k] = *(const LAS bf16x8*)(lds + PG8_SA(b, h) + aoff + m * 2048 + k * 1024); } while (0)
; #define PG8_LDB(dst, b, h) do { _Pragma("unroll") for (int n = 0; n < 2; ++n) _Pragma("unroll") for (int k = 0; k < 2; ++k) dst[n][k] = *(const LAS bf16x8*)(lds + PG8_SB(b, h) + boff + n * 2048 + k * 1024); } while (0)
; #define PG8_MMA(ai, bj, At, Bt_) do { __builtin_amdgcn_s_setprio(1); _Pragma("unroll") for (int m = 0; m < 4; ++m) _Pragma("unroll") for (int n = 0; n < 2; ++n) _Pragma("unroll") for (int k = 0; k < 2; ++k) \
;         acc[ai][bj][m][n] = __builtin_amdgcn_mfma_f32_16x16x32_bf16(Bt_[n][k], At[m][k], acc[ai][bj][m][n], 0, 0, 0); __builtin_amdgcn_s_setprio(0); } while (0)
; #define PG8_WAIT_V(n) asm volatile("s_waitcnt vmcnt(" #n ")" ::: "memory")
; #define PG8_WAIT_L(n) asm volatile("s_waitcnt lgkmcnt(" #n ")" ::: "memory")
; #define PG8_BAR __builtin_amdgcn_s_barrier()
; #define PG8_SCHED __builtin_amdgcn_sched_barrier(0)
; template <bool REMAP>
; DI void gemm_phase(LAS unsigned char* lds, const u16* A, int lda, const u16* Bt, int K, u16* O, int ldc, int nunits) {
;     ...
;             PG8_BAR; PG8_WAIT_L(0); PG8_MMA(1, 0, At, B0); PG8_BAR; PG8_SCHED;
;             PG8_STAGE(PG8_SB(0, 1), b2 + hstepB, voffB);
;             PG8_WAIT_V(6); PG8_BAR; PG8_MMA(1, 1, At, B1); PG8_BAR;
;             PG8_LDB(B0, 1, 0); PG8_SCHED; PG8_LDA(At, 1, 0); PG8_STAGE(PG8_SA(0, 1), a2 + hstepA, voffA);
;             PG8_WAIT_L(8); PG8_BAR; PG8_WAIT_L(0); PG8_MMA(0, 0, At, B0); PG8_BAR; PG8_SCHED;
	s_waitcnt lgkmcnt(0)
	s_waitcnt lgkmcnt(0)
	v_mfma_f32_16x16x32_bf16 v[62:65], v[148:151], v[164:167], 0
	v_mfma_f32_16x16x32_bf16 v[58:61], v[156:159], v[164:167], 0
	v_mfma_f32_16x16x32_bf16 v[54:57], v[148:151], v[192:195], 0
	v_mfma_f32_16x16x32_bf16 v[50:53], v[156:159], v[192:195], 0
	v_mfma_f32_16x16x32_bf16 v[38:41], v[148:151], v[200:203], 0
	v_mfma_f32_16x16x32_bf16 v[34:37], v[156:159], v[200:203], 0
	v_mfma_f32_16x16x32_bf16 v[22:25], v[148:151], v[208:211], 0
	v_mfma_f32_16x16x32_bf16 v[18:21], v[156:159], v[208:211], 0
	v_mfma_f32_16x16x32_bf16 v[62:65], v[152:155], v[168:171], v[62:65]
	v_mfma_f32_16x16x32_bf16 v[58:61], v[160:163], v[168:171], v[58:61]
	v_mfma_f32_16x16x32_bf16 v[54:57], v[152:155], v[196:199], v[54:57]
	v_mfma_f32_16x16x32_bf16 v[50:53], v[160:163], v[196:199], v[50:53]
	v_mfma_f32_16x16x32_bf16 v[38:41], v[152:155], v[204:207], v[38:41]
	v_mfma_f32_16x16x32_bf16 v[34:37], v[160:163], v[204:207], v[34:37]
	v_mfma_f32_16x16x32_bf16 v[22:25], v[152:155], v[212:215], v[22:25]
	v_mfma_f32_16x16x32_bf16 v[18:21], v[160:163], v[212:215], v[18:21]
	s_barrier
	s_add_u32 s56, s22, 0x40000
	s_addc_u32 s57, s23, 0
	s_add_i32 s58, s59, s26
	v_lshl_add_u64 v[148:149], s[56:57], 0, v[0:1]
	s_mov_b32 m0, s58
	s_nop 0
	global_load_lds_dwordx4 v[148:149], off
	v_lshl_add_u64 v[148:149], s[56:57], 0, v[130:131]
	s_add_i32 m0, s58, 0x2000
	s_nop 0
	global_load_lds_dwordx4 v[148:149], off
	s_waitcnt vmcnt(6)
	s_barrier
	v_mfma_f32_16x16x32_bf16 v[46:49], v[216:219], v[164:167], 0
	v_mfma_f32_16x16x32_bf16 v[42:45], v[224:227], v[164:167], 0
	v_mfma_f32_16x16x32_bf16 v[30:33], v[216:219], v[192:195], 0
	v_mfma_f32_16x16x32_bf16 v[26:29], v[224:227], v[192:195], 0
	v_mfma_f32_16x16x32_bf16 v[14:17], v[216:219], v[200:203], 0
	v_mfma_f32_16x16x32_bf16 v[10:13], v[224:227], v[200:203], 0
	v_mfma_f32_16x16x32_bf16 v[6:9], v[216:219], v[208:211], 0
	v_mfma_f32_16x16x32_bf16 v[2:5], v[224:227], v[208:211], 0
	v_mfma_f32_16x16x32_bf16 v[46:49], v[220:223], v[168:171], v[46:49]
	v_mfma_f32_16x16x32_bf16 v[42:45], v[228:231], v[168:171], v[42:45]
	v_mfma_f32_16x16x32_bf16 v[30:33], v[220:223], v[196:199], v[30:33]
	v_mfma_f32_16x16x32_bf16 v[26:29], v[228:231], v[196:199], v[26:29]
	v_mfma_f32_16x16x32_bf16 v[14:17], v[220:223], v[204:207], v[14:17]
	v_mfma_f32_16x16x32_bf16 v[10:13], v[228:231], v[204:207], v[10:13]
	v_mfma_f32_16x16x32_bf16 v[6:9], v[220:223], v[212:215], v[6:9]
	v_mfma_f32_16x16x32_bf16 v[2:5], v[228:231], v[212:215], v[2:5]
	s_add_i32 s56, 0, 0x18000
	v_add_u32_e32 v160, s56, v145
	s_barrier
	ds_read_b128 v[148:151], v160
	ds_read_b128 v[152:155], v160 offset:1024
	ds_read_b128 v[156:159], v160 offset:2048
	ds_read_b128 v[160:163], v160 offset:3072
	s_add_u32 s30, s30, 0x40000
	s_addc_u32 s31, s31, 0
	s_mov_b32 m0, s35
	v_lshl_add_u64 v[216:217], s[30:31], 0, v[134:135]
	ds_read_b128 v[164:167], v147 offset:32768
	ds_read_b128 v[168:171], v147 offset:33792
	ds_read_b128 v[192:195], v147 offset:34816
	ds_read_b128 v[196:199], v147 offset:35840
	ds_read_b128 v[200:203], v147 offset:36864
	ds_read_b128 v[204:207], v147 offset:37888
	ds_read_b128 v[208:211], v147 offset:38912
	ds_read_b128 v[212:215], v147 offset:39936
	global_load_lds_dwordx4 v[216:217], off
	v_lshl_add_u64 v[216:217], s[30:31], 0, v[132:133]
	s_mov_b32 m0, s36
	s_nop 0
	global_load_lds_dwordx4 v[216:217], off
	s_waitcnt lgkmcnt(8)
	s_barrier
	s_waitcnt lgkmcnt(0)
	s_waitcnt lgkmcnt(0)
	v_mfma_f32_16x16x32_bf16 v[126:129], v[148:151], v[164:167], v[126:129]
	v_mfma_f32_16x16x32_bf16 v[122:125], v[156:159], v[164:167], v[122:125]
	v_mfma_f32_16x16x32_bf16 v[118:121], v[148:151], v[192:195], v[118:121]
	v_mfma_f32_16x16x32_bf16 v[114:117], v[156:159], v[192:195], v[114:117]
	v_mfma_f32_16x16x32_bf16 v[102:105], v[148:151], v[200:203], v[102:105]
	v_mfma_f32_16x16x32_bf16 v[98:101], v[156:159], v[200:203], v[98:101]
	v_mfma_f32_16x16x32_bf16 v[86:89], v[148:151], v[208:211], v[86:89]
	v_mfma_f32_16x16x32_bf16 v[82:85], v[156:159], v[208:211], v[82:85]
	v_mfma_f32_16x16x32_bf16 v[126:129], v[152:155], v[168:171], v[126:129]
	v_mfma_f32_16x16x32_bf16 v[122:125], v[160:163], v[168:171], v[122:125]
	v_mfma_f32_16x16x32_bf16 v[118:121], v[152:155], v[196:199], v[118:121]
	v_mfma_f32_16x16x32_bf16 v[114:117], v[160:163], v[196:199], v[114:117]
	v_mfma_f32_16x16x32_bf16 v[102:105], v[152:155], v[204:207], v[102:105]
	v_mfma_f32_16x16x32_bf16 v[98:101], v[160:163], v[204:207], v[98:101]
	v_mfma_f32_16x16x32_bf16 v[86:89], v[152:155], v[212:215], v[86:89]
	v_mfma_f32_16x16x32_bf16 v[82:85], v[160:163], v[212:215], v[82:85]
	s_barrier
	s_add_i32 s30, 0, 0x1c000
	s_add_i32 s31, s56, s26
	v_add_u32_e32 v228, s30, v145
	v_lshl_add_u64 v[172:173], v[172:173], 0, s[18:19]
	s_mov_b32 m0, s31
	ds_read_b128 v[216:219], v228
	ds_read_b128 v[220:223], v228 offset:1024
	ds_read_b128 v[224:227], v228 offset:2048
	ds_read_b128 v[228:231], v228 offset:3072
	global_load_lds_dwordx4 v[172:173], off
	v_lshl_add_u64 v[172:173], v[232:233], 0, s[18:19]
	s_add_i32 m0, s31, 0x2000
	s_nop 0
	global_load_lds_dwordx4 v[172:173], off
	s_barrier
; #define PG8_STAGE(bufoff, gbase, voff) do { _Pragma("unroll") for (int _i = 0; _i < 2; ++_i) \
;         __builtin_amdgcn_global_load_lds((const unsigned*)((const char*)(gbase) + (voff)[_i]), (LAS unsigned*)(lds + (bufoff) + ldsw + _i * 8192), 16, 0, 0); } while (0)
; #define PG8_LDA(dst, b, h) do { _Pragma("unroll") for (int m = 0; m < 4; ++m) _Pragma("unroll") for (int k = 0; k < 2; ++k) dst[m][k] = *(const LAS bf16x8*)(lds + PG8_SA(b, h) + aoff + m * 2048 + k * 1024); } while (0)
; #define PG8_LDB(dst, b, h) do { _Pragma("unroll") for (int n = 0; n < 2; ++n) _Pragma("unroll") for (int k = 0; k < 2; ++k) dst[n][k] = *(const LAS bf16x8*)(lds + PG8_SB(b, h) + boff + n * 2048 + k * 1024); } while (0)
; #define PG8_MMA(ai, bj, At, Bt_) do { __builtin_amdgcn_s_setprio(1); _Pragma("unroll") for (int m = 0; m < 4; ++m) _Pragma("unroll") for (int n = 0; n < 2; ++n) _Pragma("unroll") for (int k = 0; k < 2; ++k) \
;         acc[ai][bj][m][n] = __builtin_amdgcn_mfma_f32_16x16x32_bf16(Bt_[n][k], At[m][k], acc[ai][bj][m][n], 0, 0, 0); __builtin_amdgcn_s_setprio(0); } while (0)
; #define PG8_WAIT_V(n) asm volatile("s_waitcnt vmcnt(" #n ")" ::: "memory")
; #define PG8_WAIT_L(n) asm volatile("s_waitcnt lgkmcnt(" #n ")" ::: "memory")
; #define PG8_BAR __builtin_amdgcn_s_barrier()
; #define PG8_SCHED __builtin_amdgcn_sched_barrier(0)
; template <bool REMAP>
; DI void gemm_phase(LAS unsigned char* lds, const u16* A, int lda, const u16* Bt, int K, u16* O, int ldc, int nunits) {
;     ...
;             PG8_LDB(B1, 1, 1); PG8_STAGE(PG8_SB(1, 0), b3, voffB);
;             PG8_BAR; PG8_WAIT_L(0); PG8_MMA(0, 1, At, B1); PG8_BAR;
;             PG8_LDA(At, 1, 1); PG8_STAGE(PG8_SA(1, 0), a3, voffA);
;             PG8_BAR; PG8_WAIT_L(0); PG8_MMA(1, 0, At, B0); PG8_BAR; PG8_SCHED;
;             PG8_STAGE(PG8_SB(1, 1), b3 + hstepB, voffB);
;             PG8_WAIT_V(6); PG8_BAR; PG8_MMA(1, 1, At, B1); PG8_BAR;
;         }
	s_waitcnt lgkmcnt(0)
	s_waitcnt lgkmcnt(0)
	v_mfma_f32_16x16x32_bf16 v[110:113], v[216:219], v[164:167], v[110:113]
	v_mfma_f32_16x16x32_bf16 v[106:109], v[224:227], v[164:167], v[106:109]
	v_mfma_f32_16x16x32_bf16 v[94:97], v[216:219], v[192:195], v[94:97]
	v_mfma_f32_16x16x32_bf16 v[90:93], v[224:227], v[192:195], v[90:93]
	v_mfma_f32_16x16x32_bf16 v[78:81], v[216:219], v[200:203], v[78:81]
	v_mfma_f32_16x16x32_bf16 v[74:77], v[224:227], v[200:203], v[74:77]
	v_mfma_f32_16x16x32_bf16 v[70:73], v[216:219], v[208:211], v[70:73]
	v_mfma_f32_16x16x32_bf16 v[66:69], v[224:227], v[208:211], v[66:69]
	v_mfma_f32_16x16x32_bf16 v[110:113], v[220:223], v[168:171], v[110:113]
	v_mfma_f32_16x16x32_bf16 v[106:109], v[228:231], v[168:171], v[106:109]
	v_mfma_f32_16x16x32_bf16 v[94:97], v[220:223], v[196:199], v[94:97]
	v_mfma_f32_16x16x32_bf16 v[90:93], v[228:231], v[196:199], v[90:93]
	v_mfma_f32_16x16x32_bf16 v[78:81], v[220:223], v[204:207], v[78:81]
	v_mfma_f32_16x16x32_bf16 v[74:77], v[228:231], v[204:207], v[74:77]
	v_mfma_f32_16x16x32_bf16 v[70:73], v[220:223], v[212:215], v[70:73]
	v_mfma_f32_16x16x32_bf16 v[66:69], v[228:231], v[212:215], v[66:69]
	s_mov_b32 m0, s37
	v_lshl_add_u64 v[172:173], s[28:29], 0, v[134:135]
	s_barrier
	ds_read_b128 v[164:167], v147 offset:49152
	ds_read_b128 v[168:171], v147 offset:50176
	ds_read_b128 v[192:195], v147 offset:51200
	ds_read_b128 v[196:199], v147 offset:52224
	ds_read_b128 v[200:203], v147 offset:53248
	ds_read_b128 v[204:207], v147 offset:54272
	ds_read_b128 v[208:211], v147 offset:55296
	ds_read_b128 v[212:215], v147 offset:56320
	global_load_lds_dwordx4 v[172:173], off
	v_lshl_add_u64 v[172:173], s[28:29], 0, v[132:133]
	s_mov_b32 m0, s38
	s_nop 0
	global_load_lds_dwordx4 v[172:173], off
	s_barrier
	s_waitcnt lgkmcnt(0)
	s_waitcnt lgkmcnt(0)
	v_mfma_f32_16x16x32_bf16 v[62:65], v[148:151], v[164:167], v[62:65]
	v_mfma_f32_16x16x32_bf16 v[58:61], v[156:159], v[164:167], v[58:61]
	v_mfma_f32_16x16x32_bf16 v[54:57], v[148:151], v[192:195], v[54:57]
	v_mfma_f32_16x16x32_bf16 v[50:53], v[156:159], v[192:195], v[50:53]
	v_mfma_f32_16x16x32_bf16 v[38:41], v[148:151], v[200:203], v[38:41]
	v_mfma_f32_16x16x32_bf16 v[34:37], v[156:159], v[200:203], v[34:37]
	v_mfma_f32_16x16x32_bf16 v[22:25], v[148:151], v[208:211], v[22:25]
	v_mfma_f32_16x16x32_bf16 v[18:21], v[156:159], v[208:211], v[18:21]
	v_mfma_f32_16x16x32_bf16 v[62:65], v[152:155], v[168:171], v[62:65]
	v_mfma_f32_16x16x32_bf16 v[58:61], v[160:163], v[168:171], v[58:61]
	v_mfma_f32_16x16x32_bf16 v[54:57], v[152:155], v[196:199], v[54:57]
	v_mfma_f32_16x16x32_bf16 v[50:53], v[160:163], v[196:199], v[50:53]
	v_mfma_f32_16x16x32_bf16 v[38:41], v[152:155], v[204:207], v[38:41]
	v_mfma_f32_16x16x32_bf16 v[34:37], v[160:163], v[204:207], v[34:37]
	v_mfma_f32_16x16x32_bf16 v[22:25], v[152:155], v[212:215], v[22:25]
	v_mfma_f32_16x16x32_bf16 v[18:21], v[160:163], v[212:215], v[18:21]
	s_barrier
	s_add_u32 s22, s22, 0x40080
	s_addc_u32 s23, s23, 0
	s_add_i32 s28, s30, s26
	v_lshl_add_u64 v[148:149], s[22:23], 0, v[0:1]
	s_mov_b32 m0, s28
	s_nop 0
	global_load_lds_dwordx4 v[148:149], off
	v_lshl_add_u64 v[148:149], s[22:23], 0, v[130:131]
	s_add_i32 m0, s28, 0x2000
	s_nop 0
	global_load_lds_dwordx4 v[148:149], off
	s_waitcnt vmcnt(6)
	s_barrier
	v_mfma_f32_16x16x32_bf16 v[46:49], v[216:219], v[164:167], v[46:49]
	v_mfma_f32_16x16x32_bf16 v[42:45], v[224:227], v[164:167], v[42:45]
	v_mfma_f32_16x16x32_bf16 v[30:33], v[216:219], v[192:195], v[30:33]
	v_mfma_f32_16x16x32_bf16 v[26:29], v[224:227], v[192:195], v[26:29]
	v_mfma_f32_16x16x32_bf16 v[14:17], v[216:219], v[200:203], v[14:17]
	v_mfma_f32_16x16x32_bf16 v[10:13], v[224:227], v[200:203], v[10:13]
	v_mfma_f32_16x16x32_bf16 v[6:9], v[216:219], v[208:211], v[6:9]
	v_mfma_f32_16x16x32_bf16 v[2:5], v[224:227], v[208:211], v[2:5]
	v_mfma_f32_16x16x32_bf16 v[46:49], v[220:223], v[168:171], v[46:49]
	v_mfma_f32_16x16x32_bf16 v[42:45], v[228:231], v[168:171], v[42:45]
	v_mfma_f32_16x16x32_bf16 v[30:33], v[220:223], v[196:199], v[30:33]
	v_mfma_f32_16x16x32_bf16 v[26:29], v[228:231], v[196:199], v[26:29]
	v_mfma_f32_16x16x32_bf16 v[14:17], v[220:223], v[204:207], v[14:17]
	v_mfma_f32_16x16x32_bf16 v[10:13], v[228:231], v[204:207], v[10:13]
	v_mfma_f32_16x16x32_bf16 v[6:9], v[220:223], v[212:215], v[6:9]
	v_mfma_f32_16x16x32_bf16 v[2:5], v[228:231], v[212:215], v[2:5]
	s_add_i32 s55, s55, 2
	s_add_u32 s20, s20, 0x100
	s_addc_u32 s21, s21, 0
	s_cmp_gt_u32 s55, 13
	s_barrier
; #define PG8_STAGE(bufoff, gbase, voff) do { _Pragma("unroll") for (int _i = 0; _i < 2; ++_i) \
;         __builtin_amdgcn_global_load_lds((const unsigned*)((const char*)(gbase) + (voff)[_i]), (LAS unsigned*)(lds + (bufoff) + ldsw + _i * 8192), 16, 0, 0); } while (0)
; #define PG8_LDA(dst, b, h) do { _Pragma("unroll") for (int m = 0; m < 4; ++m) _Pragma("unroll") for (int k = 0; k < 2; ++k) dst[m][k] = *(const LAS bf16x8*)(lds + PG8_SA(b, h) + aoff + m * 2048 + k * 1024); } while (0)
; #define PG8_LDB(dst, b, h) do { _Pragma("unroll") for (int n = 0; n < 2; ++n) _Pragma("unroll") for (int k = 0; k < 2; ++k) dst[n][k] = *(const LAS bf16x8*)(lds + PG8_SB(b, h) + boff + n * 2048 + k * 1024); } while (0)
; #define PG8_MMA(ai, bj, At, Bt_) do { __builtin_amdgcn_s_setprio(1); _Pragma("unroll") for (int m = 0; m < 4; ++m) _Pragma("unroll") for (int n = 0; n < 2; ++n) _Pragma("unroll") for (int k = 0; k < 2; ++k) \
;         acc[ai][bj][m][n] = __builtin_amdgcn_mfma_f32_16x16x32_bf16(Bt_[n][k], At[m][k], acc[ai][bj][m][n], 0, 0, 0); __builtin_amdgcn_s_setprio(0); } while (0)
; #define PG8_WAIT_L(n) asm volatile("s_waitcnt lgkmcnt(" #n ")" ::: "memory")
; #define PG8_BAR __builtin_amdgcn_s_barrier()
; #define PG8_SCHED __builtin_amdgcn_sched_barrier(0)
; template <bool REMAP>
; DI void gemm_phase(LAS unsigned char* lds, const u16* A, int lda, const u16* Bt, int K, u16* O, int ldc, int nunits) {
;     ...
;             PG8_LDB(B0, 0, 0); PG8_SCHED; PG8_LDA(At, 0, 0); PG8_STAGE(PG8_SA(1, 1), a1 + hstepA, voffA);
;             PG8_WAIT_L(8); PG8_BAR; PG8_WAIT_L(0); PG8_MMA(0, 0, At, B0); PG8_BAR; PG8_SCHED;
;             PG8_LDB(B1, 0, 1); PG8_STAGE(PG8_SB(0, 0), b2, voffB);
;             PG8_BAR; PG8_WAIT_L(0); PG8_MMA(0, 1, At, B1); PG8_BAR;
;             PG8_LDA(At, 0, 1); PG8_STAGE(PG8_SA(0, 0), a2, voffA);
;             PG8_BAR; PG8_WAIT_L(0); PG8_MMA(1, 0, At, B0); PG8_BAR; PG8_SCHED;
.LBB0_137:
	s_add_u32 s22, s10, s20
	s_addc_u32 s23, s11, s21
	s_add_u32 s30, s22, 0x100
	s_addc_u32 s31, s23, 0
	s_add_u32 s56, s51, s20
	s_addc_u32 s57, s54, s21
	s_add_u32 s22, s22, 0x180
	s_addc_u32 s23, s23, 0
	s_add_i32 s58, 0, 0x10000
	v_add_u32_e32 v160, s58, v145
	ds_read_b128 v[148:151], v160
	ds_read_b128 v[152:155], v160 offset:1024
	ds_read_b128 v[156:159], v160 offset:2048
	ds_read_b128 v[160:163], v160 offset:3072
	s_cmpk_eq_i32 s20, 0x700
	s_cselect_b32 s29, s50, s23
	s_cselect_b32 s28, s49, s22
	s_cselect_b32 s23, s7, s57
	s_cselect_b32 s22, s47, s56
	s_cselect_b32 s31, s5, s31
	s_cselect_b32 s30, s46, s30
	v_lshl_add_u64 v[172:173], v[142:143], 0, s[20:21]
	s_add_i32 m0, s27, 0xc000
	ds_read_b128 v[164:167], v147
	ds_read_b128 v[168:171], v147 offset:1024
	ds_read_b128 v[192:195], v147 offset:2048
	ds_read_b128 v[196:199], v147 offset:3072
	ds_read_b128 v[200:203], v147 offset:4096
	ds_read_b128 v[204:207], v147 offset:5120
	ds_read_b128 v[208:211], v147 offset:6144
	ds_read_b128 v[212:215], v147 offset:7168
	global_load_lds_dwordx4 v[172:173], off
	v_lshl_add_u64 v[172:173], v[140:141], 0, s[20:21]
	s_add_i32 m0, s27, 0xe000
	s_nop 0
	global_load_lds_dwordx4 v[172:173], off
	s_waitcnt lgkmcnt(8)
	s_barrier
	s_waitcnt lgkmcnt(0)
	s_waitcnt lgkmcnt(0)
	v_mfma_f32_16x16x32_bf16 v[126:129], v[148:151], v[164:167], v[126:129]
	v_mfma_f32_16x16x32_bf16 v[122:125], v[156:159], v[164:167], v[122:125]
	v_mfma_f32_16x16x32_bf16 v[118:121], v[148:151], v[192:195], v[118:121]
	v_mfma_f32_16x16x32_bf16 v[114:117], v[156:159], v[192:195], v[114:117]
	v_mfma_f32_16x16x32_bf16 v[102:105], v[148:151], v[200:203], v[102:105]
	v_mfma_f32_16x16x32_bf16 v[98:101], v[156:159], v[200:203], v[98:101]
	v_mfma_f32_16x16x32_bf16 v[86:89], v[148:151], v[208:211], v[86:89]
	v_mfma_f32_16x16x32_bf16 v[82:85], v[156:159], v[208:211], v[82:85]
	v_mfma_f32_16x16x32_bf16 v[126:129], v[152:155], v[168:171], v[126:129]
	v_mfma_f32_16x16x32_bf16 v[122:125], v[160:163], v[168:171], v[122:125]
	v_mfma_f32_16x16x32_bf16 v[118:121], v[152:155], v[196:199], v[118:121]
	v_mfma_f32_16x16x32_bf16 v[114:117], v[160:163], v[196:199], v[114:117]
	v_mfma_f32_16x16x32_bf16 v[102:105], v[152:155], v[204:207], v[102:105]
	v_mfma_f32_16x16x32_bf16 v[98:101], v[160:163], v[204:207], v[98:101]
	v_mfma_f32_16x16x32_bf16 v[86:89], v[152:155], v[212:215], v[86:89]
	v_mfma_f32_16x16x32_bf16 v[82:85], v[160:163], v[212:215], v[82:85]
	s_barrier
	s_add_i32 s59, 0, 0x14000
	v_add_u32_e32 v172, s59, v145
	s_add_i32 s56, s58, s26
	ds_read_b128 v[216:219], v172
	ds_read_b128 v[220:223], v172 offset:1024
	ds_read_b128 v[224:227], v172 offset:2048
	ds_read_b128 v[228:231], v172 offset:3072
	v_lshl_add_u64 v[172:173], s[22:23], 0, v[0:1]
	s_mov_b32 m0, s56
	v_lshl_add_u64 v[232:233], s[22:23], 0, v[130:131]
	global_load_lds_dwordx4 v[172:173], off
	s_add_i32 m0, s56, 0x2000
	s_nop 0
	global_load_lds_dwordx4 v[232:233], off
	s_barrier
	s_waitcnt lgkmcnt(0)
	s_waitcnt lgkmcnt(0)
	v_mfma_f32_16x16x32_bf16 v[110:113], v[216:219], v[164:167], v[110:113]
	v_mfma_f32_16x16x32_bf16 v[106:109], v[224:227], v[164:167], v[106:109]
	v_mfma_f32_16x16x32_bf16 v[94:97], v[216:219], v[192:195], v[94:97]
	v_mfma_f32_16x16x32_bf16 v[90:93], v[224:227], v[192:195], v[90:93]
	v_mfma_f32_16x16x32_bf16 v[78:81], v[216:219], v[200:203], v[78:81]
	v_mfma_f32_16x16x32_bf16 v[74:77], v[224:227], v[200:203], v[74:77]
	v_mfma_f32_16x16x32_bf16 v[70:73], v[216:219], v[208:211], v[70:73]
	v_mfma_f32_16x16x32_bf16 v[66:69], v[224:227], v[208:211], v[66:69]
	v_mfma_f32_16x16x32_bf16 v[110:113], v[220:223], v[168:171], v[110:113]
	v_mfma_f32_16x16x32_bf16 v[106:109], v[228:231], v[168:171], v[106:109]
	v_mfma_f32_16x16x32_bf16 v[94:97], v[220:223], v[196:199], v[94:97]
	v_mfma_f32_16x16x32_bf16 v[90:93], v[228:231], v[196:199], v[90:93]
	v_mfma_f32_16x16x32_bf16 v[78:81], v[220:223], v[204:207], v[78:81]
	v_mfma_f32_16x16x32_bf16 v[74:77], v[228:231], v[204:207], v[74:77]
	v_mfma_f32_16x16x32_bf16 v[70:73], v[220:223], v[212:215], v[70:73]
	v_mfma_f32_16x16x32_bf16 v[66:69], v[228:231], v[212:215], v[66:69]
	s_mov_b32 m0, s27
	v_lshl_add_u64 v[234:235], s[30:31], 0, v[134:135]
	s_barrier
	ds_read_b128 v[164:167], v147 offset:16384
	ds_read_b128 v[168:171], v147 offset:17408
	ds_read_b128 v[192:195], v147 offset:18432
	ds_read_b128 v[196:199], v147 offset:19456
	ds_read_b128 v[200:203], v147 offset:20480
	ds_read_b128 v[204:207], v147 offset:21504
	ds_read_b128 v[208:211], v147 offset:22528
	ds_read_b128 v[212:215], v147 offset:23552
	global_load_lds_dwordx4 v[234:235], off
	v_lshl_add_u64 v[234:235], s[30:31], 0, v[132:133]
	s_mov_b32 m0, s34
	s_nop 0
	global_load_lds_dwordx4 v[234:235], off
	s_barrier
	s_waitcnt lgkmcnt(0)
	s_waitcnt lgkmcnt(0)
	v_mfma_f32_16x16x32_bf16 v[62:65], v[148:151], v[164:167], v[62:65]
	v_mfma_f32_16x16x32_bf16 v[58:61], v[156:159], v[164:167], v[58:61]
	v_mfma_f32_16x16x32_bf16 v[54:57], v[148:151], v[192:195], v[54:57]
	v_mfma_f32_16x16x32_bf16 v[50:53], v[156:159], v[192:195], v[50:53]
	v_mfma_f32_16x16x32_bf16 v[38:41], v[148:151], v[200:203], v[38:41]
	v_mfma_f32_16x16x32_bf16 v[34:37], v[156:159], v[200:203], v[34:37]
	v_mfma_f32_16x16x32_bf16 v[22:25], v[148:151], v[208:211], v[22:25]
	v_mfma_f32_16x16x32_bf16 v[18:21], v[156:159], v[208:211], v[18:21]
	v_mfma_f32_16x16x32_bf16 v[62:65], v[152:155], v[168:171], v[62:65]
	v_mfma_f32_16x16x32_bf16 v[58:61], v[160:163], v[168:171], v[58:61]
	v_mfma_f32_16x16x32_bf16 v[54:57], v[152:155], v[196:199], v[54:57]
	v_mfma_f32_16x16x32_bf16 v[50:53], v[160:163], v[196:199], v[50:53]
	v_mfma_f32_16x16x32_bf16 v[38:41], v[152:155], v[204:207], v[38:41]
	v_mfma_f32_16x16x32_bf16 v[34:37], v[160:163], v[204:207], v[34:37]
	v_mfma_f32_16x16x32_bf16 v[22:25], v[152:155], v[212:215], v[22:25]
	v_mfma_f32_16x16x32_bf16 v[18:21], v[160:163], v[212:215], v[18:21]
	s_barrier
; #define PG8_STAGE(bufoff, gbase, voff) do { _Pragma("unroll") for (int _i = 0; _i < 2; ++_i) \
;         __builtin_amdgcn_global_load_lds((const unsigned*)((const char*)(gbase) + (voff)[_i]), (LAS unsigned*)(lds + (bufoff) + ldsw + _i * 8192), 16, 0, 0); } while (0)
; #define PG8_LDA(dst, b, h) do { _Pragma("unroll") for (int m = 0; m < 4; ++m) _Pragma("unroll") for (int k = 0; k < 2; ++k) dst[m][k] = *(const LAS bf16x8*)(lds + PG8_SA(b, h) + aoff + m * 2048 + k * 1024); } while (0)
; #define PG8_LDB(dst, b, h) do { _Pragma("unroll") for (int n = 0; n < 2; ++n) _Pragma("unroll") for (int k = 0; k < 2; ++k) dst[n][k] = *(const LAS bf16x8*)(lds + PG8_SB(b, h) + boff + n * 2048 + k * 1024); } while (0)
; #define PG8_MMA(ai, bj, At, Bt_) do { __builtin_amdgcn_s_setprio(1); _Pragma("unroll") for (int m = 0; m < 4; ++m) _Pragma("unroll") for (int n = 0; n < 2; ++n) _Pragma("unroll") for (int k = 0; k < 2; ++k) \
;         acc[ai][bj][m][n] = __builtin_amdgcn_mfma_f32_16x16x32_bf16(Bt_[n][k], At[m][k], acc[ai][bj][m][n], 0, 0, 0); __builtin_amdgcn_s_setprio(0); } while (0)
; #define PG8_WAIT_V(n) asm volatile("s_waitcnt vmcnt(" #n ")" ::: "memory")
; #define PG8_WAIT_L(n) asm volatile("s_waitcnt lgkmcnt(" #n ")" ::: "memory")
; #define PG8_BAR __builtin_amdgcn_s_barrier()
; #define PG8_SCHED __builtin_amdgcn_sched_barrier(0)
; template <bool REMAP>
; DI void gemm_phase(LAS unsigned char* lds, const u16* A, int lda, const u16* Bt, int K, u16* O, int ldc, int nunits) {
;     ...
;             PG8_STAGE(PG8_SB(0, 1), b2 + hstepB, voffB);
;             PG8_WAIT_V(6); PG8_BAR; PG8_MMA(1, 1, At, B1); PG8_BAR;
;             PG8_LDB(B0, 1, 0); PG8_SCHED; PG8_LDA(At, 1, 0); PG8_STAGE(PG8_SA(0, 1), a2 + hstepA, voffA);
;             PG8_WAIT_L(8); PG8_BAR; PG8_WAIT_L(0); PG8_MMA(0, 0, At, B0); PG8_BAR; PG8_SCHED;
;             PG8_LDB(B1, 1, 1); PG8_STAGE(PG8_SB(1, 0), b3, voffB);
;             PG8_BAR; PG8_WAIT_L(0); PG8_MMA(0, 1, At, B1); PG8_BAR;
;             PG8_LDA(At, 1, 1); PG8_STAGE(PG8_SA(1, 0), a3, voffA);
	s_add_u32 s56, s22, 0x40000
	s_addc_u32 s57, s23, 0
	s_add_i32 s58, s59, s26
	v_lshl_add_u64 v[148:149], s[56:57], 0, v[0:1]
	s_mov_b32 m0, s58
	s_nop 0
	global_load_lds_dwordx4 v[148:149], off
	v_lshl_add_u64 v[148:149], s[56:57], 0, v[130:131]
	s_add_i32 m0, s58, 0x2000
	s_nop 0
	global_load_lds_dwordx4 v[148:149], off
	s_waitcnt vmcnt(6)
	s_barrier
	v_mfma_f32_16x16x32_bf16 v[46:49], v[216:219], v[164:167], v[46:49]
	v_mfma_f32_16x16x32_bf16 v[42:45], v[224:227], v[164:167], v[42:45]
	v_mfma_f32_16x16x32_bf16 v[30:33], v[216:219], v[192:195], v[30:33]
	v_mfma_f32_16x16x32_bf16 v[26:29], v[224:227], v[192:195], v[26:29]
	v_mfma_f32_16x16x32_bf16 v[14:17], v[216:219], v[200:203], v[14:17]
	v_mfma_f32_16x16x32_bf16 v[10:13], v[224:227], v[200:203], v[10:13]
	v_mfma_f32_16x16x32_bf16 v[6:9], v[216:219], v[208:211], v[6:9]
	v_mfma_f32_16x16x32_bf16 v[2:5], v[224:227], v[208:211], v[2:5]
	v_mfma_f32_16x16x32_bf16 v[46:49], v[220:223], v[168:171], v[46:49]
	v_mfma_f32_16x16x32_bf16 v[42:45], v[228:231], v[168:171], v[42:45]
	v_mfma_f32_16x16x32_bf16 v[30:33], v[220:223], v[196:199], v[30:33]
	v_mfma_f32_16x16x32_bf16 v[26:29], v[228:231], v[196:199], v[26:29]
	v_mfma_f32_16x16x32_bf16 v[14:17], v[220:223], v[204:207], v[14:17]
	v_mfma_f32_16x16x32_bf16 v[10:13], v[228:231], v[204:207], v[10:13]
	v_mfma_f32_16x16x32_bf16 v[6:9], v[220:223], v[212:215], v[6:9]
	v_mfma_f32_16x16x32_bf16 v[2:5], v[228:231], v[212:215], v[2:5]
	s_add_i32 s56, 0, 0x18000
	v_add_u32_e32 v160, s56, v145
	s_barrier
	ds_read_b128 v[148:151], v160
	ds_read_b128 v[152:155], v160 offset:1024
	ds_read_b128 v[156:159], v160 offset:2048
	ds_read_b128 v[160:163], v160 offset:3072
	s_add_u32 s30, s30, 0x40000
	s_addc_u32 s31, s31, 0
	s_mov_b32 m0, s35
	v_lshl_add_u64 v[216:217], s[30:31], 0, v[134:135]
	ds_read_b128 v[164:167], v147 offset:32768
	ds_read_b128 v[168:171], v147 offset:33792
	ds_read_b128 v[192:195], v147 offset:34816
	ds_read_b128 v[196:199], v147 offset:35840
	ds_read_b128 v[200:203], v147 offset:36864
	ds_read_b128 v[204:207], v147 offset:37888
	ds_read_b128 v[208:211], v147 offset:38912
	ds_read_b128 v[212:215], v147 offset:39936
	global_load_lds_dwordx4 v[216:217], off
	v_lshl_add_u64 v[216:217], s[30:31], 0, v[132:133]
	s_mov_b32 m0, s36
	s_nop 0
	global_load_lds_dwordx4 v[216:217], off
	s_waitcnt lgkmcnt(8)
	s_barrier
	s_waitcnt lgkmcnt(0)
	s_waitcnt lgkmcnt(0)
	v_mfma_f32_16x16x32_bf16 v[126:129], v[148:151], v[164:167], v[126:129]
	v_mfma_f32_16x16x32_bf16 v[122:125], v[156:159], v[164:167], v[122:125]
	v_mfma_f32_16x16x32_bf16 v[118:121], v[148:151], v[192:195], v[118:121]
	v_mfma_f32_16x16x32_bf16 v[114:117], v[156:159], v[192:195], v[114:117]
	v_mfma_f32_16x16x32_bf16 v[102:105], v[148:151], v[200:203], v[102:105]
	v_mfma_f32_16x16x32_bf16 v[98:101], v[156:159], v[200:203], v[98:101]
	v_mfma_f32_16x16x32_bf16 v[86:89], v[148:151], v[208:211], v[86:89]
	v_mfma_f32_16x16x32_bf16 v[82:85], v[156:159], v[208:211], v[82:85]
	v_mfma_f32_16x16x32_bf16 v[126:129], v[152:155], v[168:171], v[126:129]
	v_mfma_f32_16x16x32_bf16 v[122:125], v[160:163], v[168:171], v[122:125]
	v_mfma_f32_16x16x32_bf16 v[118:121], v[152:155], v[196:199], v[118:121]
	v_mfma_f32_16x16x32_bf16 v[114:117], v[160:163], v[196:199], v[114:117]
	v_mfma_f32_16x16x32_bf16 v[102:105], v[152:155], v[204:207], v[102:105]
	v_mfma_f32_16x16x32_bf16 v[98:101], v[160:163], v[204:207], v[98:101]
	v_mfma_f32_16x16x32_bf16 v[86:89], v[152:155], v[212:215], v[86:89]
	v_mfma_f32_16x16x32_bf16 v[82:85], v[160:163], v[212:215], v[82:85]
	s_barrier
	s_add_i32 s30, 0, 0x1c000
	s_add_i32 s31, s56, s26
	v_add_u32_e32 v228, s30, v145
	v_lshl_add_u64 v[172:173], v[172:173], 0, s[18:19]
	s_mov_b32 m0, s31
	ds_read_b128 v[216:219], v228
	ds_read_b128 v[220:223], v228 offset:1024
	ds_read_b128 v[224:227], v228 offset:2048
	ds_read_b128 v[228:231], v228 offset:3072
	global_load_lds_dwordx4 v[172:173], off
	v_lshl_add_u64 v[172:173], v[232:233], 0, s[18:19]
	s_add_i32 m0, s31, 0x2000
	s_nop 0
	global_load_lds_dwordx4 v[172:173], off
	s_barrier
	s_waitcnt lgkmcnt(0)
	s_waitcnt lgkmcnt(0)
	v_mfma_f32_16x16x32_bf16 v[110:113], v[216:219], v[164:167], v[110:113]
	v_mfma_f32_16x16x32_bf16 v[106:109], v[224:227], v[164:167], v[106:109]
	v_mfma_f32_16x16x32_bf16 v[94:97], v[216:219], v[192:195], v[94:97]
	v_mfma_f32_16x16x32_bf16 v[90:93], v[224:227], v[192:195], v[90:93]
	v_mfma_f32_16x16x32_bf16 v[78:81], v[216:219], v[200:203], v[78:81]
	v_mfma_f32_16x16x32_bf16 v[74:77], v[224:227], v[200:203], v[74:77]
	v_mfma_f32_16x16x32_bf16 v[70:73], v[216:219], v[208:211], v[70:73]
	v_mfma_f32_16x16x32_bf16 v[66:69], v[224:227], v[208:211], v[66:69]
	v_mfma_f32_16x16x32_bf16 v[110:113], v[220:223], v[168:171], v[110:113]
	v_mfma_f32_16x16x32_bf16 v[106:109], v[228:231], v[168:171], v[106:109]
	v_mfma_f32_16x16x32_bf16 v[94:97], v[220:223], v[196:199], v[94:97]
	v_mfma_f32_16x16x32_bf16 v[90:93], v[228:231], v[196:199], v[90:93]
	v_mfma_f32_16x16x32_bf16 v[78:81], v[220:223], v[204:207], v[78:81]
	v_mfma_f32_16x16x32_bf16 v[74:77], v[228:231], v[204:207], v[74:77]
	v_mfma_f32_16x16x32_bf16 v[70:73], v[220:223], v[212:215], v[70:73]
	v_mfma_f32_16x16x32_bf16 v[66:69], v[228:231], v[212:215], v[66:69]
	s_mov_b32 m0, s37
	v_lshl_add_u64 v[172:173], s[28:29], 0, v[134:135]
	s_barrier
	ds_read_b128 v[164:167], v147 offset:49152
	ds_read_b128 v[168:171], v147 offset:50176
	ds_read_b128 v[192:195], v147 offset:51200
	ds_read_b128 v[196:199], v147 offset:52224
	ds_read_b128 v[200:203], v147 offset:53248
	ds_read_b128 v[204:207], v147 offset:54272
	ds_read_b128 v[208:211], v147 offset:55296
	ds_read_b128 v[212:215], v147 offset:56320
	global_load_lds_dwordx4 v[172:173], off
	v_lshl_add_u64 v[172:173], s[28:29], 0, v[132:133]
	s_mov_b32 m0, s38
	s_nop 0
	global_load_lds_dwordx4 v[172:173], off
	s_barrier
; DI unsigned pk2(float lo, float hi) { fl2_t f = {lo, hi}; bf2_t b = __builtin_convertvector(f, bf2_t); return __builtin_bit_cast(unsigned, b); }
; #define PG8_STAGE(bufoff, gbase, voff) do { _Pragma("unroll") for (int _i = 0; _i < 2; ++_i) \
;         __builtin_amdgcn_global_load_lds((const unsigned*)((const char*)(gbase) + (voff)[_i]), (LAS unsigned*)(lds + (bufoff) + ldsw + _i * 8192), 16, 0, 0); } while (0)
; #define PG8_MMA(ai, bj, At, Bt_) do { __builtin_amdgcn_s_setprio(1); _Pragma("unroll") for (int m = 0; m < 4; ++m) _Pragma("unroll") for (int n = 0; n < 2; ++n) _Pragma("unroll") for (int k = 0; k < 2; ++k) \
;         acc[ai][bj][m][n] = __builtin_amdgcn_mfma_f32_16x16x32_bf16(Bt_[n][k], At[m][k], acc[ai][bj][m][n], 0, 0, 0); __builtin_amdgcn_s_setprio(0); } while (0)
; #define PG8_WAIT_V(n) asm volatile("s_waitcnt vmcnt(" #n ")" ::: "memory")
; #define PG8_WAIT_L(n) asm volatile("s_waitcnt lgkmcnt(" #n ")" ::: "memory")
; template <bool REMAP>
; DI void gemm_phase(LAS unsigned char* lds, const u16* A, int lda, const u16* Bt, int K, u16* O, int ldc, int nunits) {
;     ...
;             PG8_BAR; PG8_WAIT_L(0); PG8_MMA(1, 0, At, B0); PG8_BAR; PG8_SCHED;
;             PG8_STAGE(PG8_SB(1, 1), b3 + hstepB, voffB);
;             PG8_WAIT_V(6); PG8_BAR; PG8_MMA(1, 1, At, B1); PG8_BAR;
;         }
;         {
;             const int row0 = cur.pm * BM + wr * 64 + fr, col0 = cur.pn * BM + wc * 32 + 8 * fq;
; #pragma unroll
;             for (int ai = 0; ai < 2; ++ai)
; #pragma unroll
;                 for (int m = 0; m < 4; ++m) { u16* rowp = O + (size_t)(row0 + ai * HALF + m * 16) * ldc + col0;
; #pragma unroll
;                     for (int bj = 0; bj < 2; ++bj) { const f32x4 v0 = acc[ai][bj][m][0], v1 = acc[ai][bj][m][1];
;                         u32x4 w = {pk2(v0[0], v0[1]), pk2(v0[2], v0[3]), pk2(v1[0], v1[1]), pk2(v1[2], v1[3])};
;                         *(u32x4*)(rowp + bj * HALF) = w; } }
;         }
;         if (!has_next) break;
; #pragma unroll
;         for (int a = 0; a < 2; ++a)
; #pragma unroll
;             for (int b = 0; b < 2; ++b)
; #pragma unroll
;                 for (int m = 0; m < 4; ++m)
; #pragma unroll
;                     for (int n = 0; n < 2; ++n) acc[a][b][m][n] = (f32x4){0.f, 0.f, 0.f, 0.f};
;         cur = nxt; cA = nA; cB = nB; ++ui;
;     }
;     PG8_WAIT_V(0);
;     if (wr == 0) PG8_BAR;
;     PG8_BAR;
	s_waitcnt lgkmcnt(0)
	s_waitcnt lgkmcnt(0)
	v_mfma_f32_16x16x32_bf16 v[62:65], v[148:151], v[164:167], v[62:65]
	v_mfma_f32_16x16x32_bf16 v[58:61], v[156:159], v[164:167], v[58:61]
	v_mfma_f32_16x16x32_bf16 v[54:57], v[148:151], v[192:195], v[54:57]
	v_mfma_f32_16x16x32_bf16 v[50:53], v[156:159], v[192:195], v[50:53]
	v_mfma_f32_16x16x32_bf16 v[38:41], v[148:151], v[200:203], v[38:41]
	v_mfma_f32_16x16x32_bf16 v[34:37], v[156:159], v[200:203], v[34:37]
	v_mfma_f32_16x16x32_bf16 v[22:25], v[148:151], v[208:211], v[22:25]
	v_mfma_f32_16x16x32_bf16 v[18:21], v[156:159], v[208:211], v[18:21]
	v_mfma_f32_16x16x32_bf16 v[62:65], v[152:155], v[168:171], v[62:65]
	v_mfma_f32_16x16x32_bf16 v[58:61], v[160:163], v[168:171], v[58:61]
	v_mfma_f32_16x16x32_bf16 v[54:57], v[152:155], v[196:199], v[54:57]
	v_mfma_f32_16x16x32_bf16 v[50:53], v[160:163], v[196:199], v[50:53]
	v_mfma_f32_16x16x32_bf16 v[38:41], v[152:155], v[204:207], v[38:41]
	v_mfma_f32_16x16x32_bf16 v[34:37], v[160:163], v[204:207], v[34:37]
	v_mfma_f32_16x16x32_bf16 v[22:25], v[152:155], v[212:215], v[22:25]
	v_mfma_f32_16x16x32_bf16 v[18:21], v[160:163], v[212:215], v[18:21]
	s_barrier
	s_add_u32 s22, s22, 0x40080
	s_addc_u32 s23, s23, 0
	s_add_i32 s28, s30, s26
	v_lshl_add_u64 v[148:149], s[22:23], 0, v[0:1]
	s_mov_b32 m0, s28
	s_nop 0
	global_load_lds_dwordx4 v[148:149], off
	v_lshl_add_u64 v[148:149], s[22:23], 0, v[130:131]
	s_add_i32 m0, s28, 0x2000
	s_nop 0
	global_load_lds_dwordx4 v[148:149], off
	s_waitcnt vmcnt(6)
	s_barrier
	v_mfma_f32_16x16x32_bf16 v[46:49], v[216:219], v[164:167], v[46:49]
	v_mfma_f32_16x16x32_bf16 v[42:45], v[224:227], v[164:167], v[42:45]
	v_mfma_f32_16x16x32_bf16 v[30:33], v[216:219], v[192:195], v[30:33]
	v_mfma_f32_16x16x32_bf16 v[26:29], v[224:227], v[192:195], v[26:29]
	v_mfma_f32_16x16x32_bf16 v[14:17], v[216:219], v[200:203], v[14:17]
	v_mfma_f32_16x16x32_bf16 v[10:13], v[224:227], v[200:203], v[10:13]
	v_mfma_f32_16x16x32_bf16 v[6:9], v[216:219], v[208:211], v[6:9]
	v_mfma_f32_16x16x32_bf16 v[2:5], v[224:227], v[208:211], v[2:5]
	v_mfma_f32_16x16x32_bf16 v[46:49], v[220:223], v[168:171], v[46:49]
	v_mfma_f32_16x16x32_bf16 v[42:45], v[228:231], v[168:171], v[42:45]
	v_mfma_f32_16x16x32_bf16 v[30:33], v[220:223], v[196:199], v[30:33]
	v_mfma_f32_16x16x32_bf16 v[26:29], v[228:231], v[196:199], v[26:29]
	v_mfma_f32_16x16x32_bf16 v[14:17], v[220:223], v[204:207], v[14:17]
	v_mfma_f32_16x16x32_bf16 v[10:13], v[228:231], v[204:207], v[10:13]
	v_mfma_f32_16x16x32_bf16 v[6:9], v[220:223], v[212:215], v[6:9]
	v_mfma_f32_16x16x32_bf16 v[2:5], v[228:231], v[212:215], v[2:5]
	s_add_i32 s55, s55, 2
	s_add_u32 s20, s20, 0x100
	s_addc_u32 s21, s21, 0
	s_cmp_gt_u32 s55, 13
	s_barrier
	s_cbranch_scc0 .LBB0_137
	v_lshl_or_b32 v140, s40, 8, v146
	v_lshl_add_u32 v148, s41, 8, v144
	v_ashrrev_i32_e32 v141, 31, v140
	v_lshl_add_u64 v[140:141], v[140:141], 1, s[0:1]
	v_cvt_pk_bf16_f32 v70, v70, v71
	v_cvt_pk_bf16_f32 v71, v72, v73
	v_cvt_pk_bf16_f32 v72, v66, v67
	v_add_u32_e32 v66, 0x80, v148
	v_mad_i64_i32 v[142:143], s[10:11], v148, s52, v[140:141]
	v_cvt_pk_bf16_f32 v110, v110, v111
	v_cvt_pk_bf16_f32 v111, v112, v113
	v_cvt_pk_bf16_f32 v112, v106, v107
	v_cvt_pk_bf16_f32 v113, v108, v109
	v_or_b32_e32 v106, 16, v148
	v_mad_i64_i32 v[66:67], s[10:11], v66, s52, v[140:141]
	v_cvt_pk_bf16_f32 v46, v46, v47
	v_cvt_pk_bf16_f32 v47, v48, v49
	v_cvt_pk_bf16_f32 v48, v42, v43
	v_cvt_pk_bf16_f32 v49, v44, v45
	v_add_u32_e32 v42, 0x90, v148
	flat_store_dwordx4 v[142:143], v[110:113] offset:256
	v_cvt_pk_bf16_f32 v94, v94, v95
	v_cvt_pk_bf16_f32 v95, v96, v97
	v_mad_i64_i32 v[110:111], s[10:11], v106, s52, v[140:141]
	v_cvt_pk_bf16_f32 v96, v90, v91
	v_cvt_pk_bf16_f32 v97, v92, v93
	v_or_b32_e32 v90, 32, v148
	flat_store_dwordx4 v[66:67], v[46:49] offset:256
	v_cvt_pk_bf16_f32 v30, v30, v31
	v_cvt_pk_bf16_f32 v31, v32, v33
	v_mad_i64_i32 v[46:47], s[10:11], v42, s52, v[140:141]
	v_cvt_pk_bf16_f32 v32, v26, v27
	v_cvt_pk_bf16_f32 v33, v28, v29
	v_add_u32_e32 v26, 0xa0, v148
	flat_store_dwordx4 v[110:111], v[94:97] offset:256
	v_cvt_pk_bf16_f32 v78, v78, v79
	v_cvt_pk_bf16_f32 v79, v80, v81
	v_mad_i64_i32 v[94:95], s[10:11], v90, s52, v[140:141]
	v_cvt_pk_bf16_f32 v80, v74, v75
	v_cvt_pk_bf16_f32 v81, v76, v77
	v_or_b32_e32 v74, 48, v148
	flat_store_dwordx4 v[46:47], v[30:33] offset:256
	v_cvt_pk_bf16_f32 v14, v14, v15
	v_cvt_pk_bf16_f32 v15, v16, v17
	v_mad_i64_i32 v[30:31], s[10:11], v26, s52, v[140:141]
	v_cvt_pk_bf16_f32 v16, v10, v11
	v_cvt_pk_bf16_f32 v17, v12, v13
	v_add_u32_e32 v10, 0xb0, v148
	flat_store_dwordx4 v[94:95], v[78:81] offset:256
	flat_store_dwordx4 v[30:31], v[14:17] offset:256
	v_cvt_pk_bf16_f32 v126, v126, v127
	v_mad_i64_i32 v[78:79], s[10:11], v74, s52, v[140:141]
	v_mad_i64_i32 v[14:15], s[10:11], v10, s52, v[140:141]
	v_cvt_pk_bf16_f32 v127, v128, v129
	v_cvt_pk_bf16_f32 v128, v122, v123
	v_cvt_pk_bf16_f32 v129, v124, v125
	v_cvt_pk_bf16_f32 v106, v118, v119
	v_cvt_pk_bf16_f32 v107, v120, v121
	v_cvt_pk_bf16_f32 v108, v114, v115
	v_cvt_pk_bf16_f32 v109, v116, v117
	v_cvt_pk_bf16_f32 v90, v102, v103
	v_cvt_pk_bf16_f32 v91, v104, v105
	v_cvt_pk_bf16_f32 v92, v98, v99
	v_cvt_pk_bf16_f32 v93, v100, v101
	v_cvt_pk_bf16_f32 v74, v86, v87
	v_cvt_pk_bf16_f32 v75, v88, v89
	v_cvt_pk_bf16_f32 v76, v82, v83
	v_cvt_pk_bf16_f32 v77, v84, v85
	v_cvt_pk_bf16_f32 v73, v68, v69
	v_cvt_pk_bf16_f32 v62, v62, v63
	v_cvt_pk_bf16_f32 v63, v64, v65
	v_cvt_pk_bf16_f32 v64, v58, v59
	v_cvt_pk_bf16_f32 v65, v60, v61
	v_cvt_pk_bf16_f32 v42, v54, v55
	v_cvt_pk_bf16_f32 v43, v56, v57
	v_cvt_pk_bf16_f32 v44, v50, v51
	v_cvt_pk_bf16_f32 v45, v52, v53
	v_cvt_pk_bf16_f32 v26, v38, v39
	v_cvt_pk_bf16_f32 v27, v40, v41
	v_cvt_pk_bf16_f32 v28, v34, v35
	v_cvt_pk_bf16_f32 v29, v36, v37
	v_cvt_pk_bf16_f32 v10, v22, v23
	v_cvt_pk_bf16_f32 v11, v24, v25
	v_cvt_pk_bf16_f32 v12, v18, v19
	v_cvt_pk_bf16_f32 v13, v20, v21
	v_cvt_pk_bf16_f32 v6, v6, v7
	v_cvt_pk_bf16_f32 v7, v8, v9
	v_cvt_pk_bf16_f32 v8, v2, v3
	v_cvt_pk_bf16_f32 v9, v4, v5
	s_and_b64 vcc, exec, s[8:9]
	s_mov_b32 s40, s6
	s_mov_b32 s41, s4
	s_mov_b64 s[20:21], s[14:15]
	s_mov_b64 s[10:11], s[12:13]
	flat_store_dwordx4 v[142:143], v[126:129]
	flat_store_dwordx4 v[110:111], v[106:109]
	flat_store_dwordx4 v[94:95], v[90:93]
	flat_store_dwordx4 v[78:79], v[74:77]
	flat_store_dwordx4 v[78:79], v[70:73] offset:256
	flat_store_dwordx4 v[66:67], v[62:65]
	flat_store_dwordx4 v[46:47], v[42:45]
	flat_store_dwordx4 v[30:31], v[26:29]
	flat_store_dwordx4 v[14:15], v[10:13]
	flat_store_dwordx4 v[14:15], v[6:9] offset:256
	s_cbranch_vccz .LBB0_134
	s_waitcnt vmcnt(0)
	s_cmpk_gt_u32 s2, 0xff
	s_cbranch_scc1 .LBB0_141
	s_barrier

; #define PG8_STAGE(bufoff, gbase, voff) do { _Pragma("unroll") for (int _i = 0; _i < 2; ++_i) \
;         __builtin_amdgcn_global_load_lds((const unsigned*)((const char*)(gbase) + (voff)[_i]), (LAS unsigned*)(lds + (bufoff) + ldsw + _i * 8192), 16, 0, 0); } while (0)
; #define PG8_LDA(dst, b, h) do { _Pragma("unroll") for (int m = 0; m < 4; ++m) _Pragma("unroll") for (int k = 0; k < 2; ++k) dst[m][k] = *(const LAS bf16x8*)(lds + PG8_SA(b, h) + aoff + m * 2048 + k * 1024); } while (0)
; #define PG8_LDB(dst, b, h) do { _Pragma("unroll") for (int n = 0; n < 2; ++n) _Pragma("unroll") for (int k = 0; k < 2; ++k) dst[n][k] = *(const LAS bf16x8*)(lds + PG8_SB(b, h) + boff + n * 2048 + k * 1024); } while (0)
; #define PG8_MMA(ai, bj, At, Bt_) do { __builtin_amdgcn_s_setprio(1); _Pragma("unroll") for (int m = 0; m < 4; ++m) _Pragma("unroll") for (int n = 0; n < 2; ++n) _Pragma("unroll") for (int k = 0; k < 2; ++k) \
;         acc[ai][bj][m][n] = __builtin_amdgcn_mfma_f32_16x16x32_bf16(Bt_[n][k], At[m][k], acc[ai][bj][m][n], 0, 0, 0); __builtin_amdgcn_s_setprio(0); } while (0)
; #define PG8_WAIT_L(n) asm volatile("s_waitcnt lgkmcnt(" #n ")" ::: "memory")
; #define PG8_BAR __builtin_amdgcn_s_barrier()
; template <bool REMAP>
; DI void gemm_phase(LAS unsigned char* lds, const u16* A, int lda, const u16* Bt, int K, u16* O, int ldc, int nunits) {
;     ...
;     auto akb = [&](int kt) -> size_t { const int k0 = kt * BK; return (size_t)(REMAP ? (k0 < 768 ? k0 : (k0 < 1536 ? k0 + 384 : k0 + 1920)) : k0) * 2; };
;     ...
;         for (int t = 0; t < nt; t += 2) {
;             const bool last = (t == nt - 2);
;             const char* a1 = cA + akb(t + 1);
;             const char* a2 = last ? nA + akb(0) : cA + akb(t + 2); const char* b2 = last ? nB : cB + (size_t)(t + 2) * kstep;
;             const char* a3 = last ? nA + akb(1) : cA + akb(t + 3); const char* b3 = b2 + kstep;
;             PG8_LDB(B0, 0, 0); PG8_SCHED; PG8_LDA(At, 0, 0); PG8_STAGE(PG8_SA(1, 1), a1 + hstepA, voffA);
;             PG8_WAIT_L(8); PG8_BAR; PG8_WAIT_L(0); PG8_MMA(0, 0, At, B0); PG8_BAR; PG8_SCHED;
;             PG8_LDB(B1, 0, 1); PG8_STAGE(PG8_SB(0, 0), b2, voffB);
;             PG8_BAR; PG8_WAIT_L(0); PG8_MMA(0, 1, At, B1); PG8_BAR;
;             PG8_LDA(At, 0, 1); PG8_STAGE(PG8_SA(0, 0), a2, voffA);
;             PG8_BAR; PG8_WAIT_L(0); PG8_MMA(1, 0, At, B0); PG8_BAR; PG8_SCHED;
.LBB0_387:
	s_and_b64 s[20:21], exec, s[20:21]
	s_cselect_b32 s21, s5, s47
	s_cselect_b32 s20, s41, s46
	s_cmp_lt_u32 s50, 24
	s_cselect_b32 s51, 0x180, s68
	s_cmp_gt_u32 s50, 11
	s_cselect_b32 s51, s51, 0
	s_add_i32 s51, s51, s49
	s_lshl_b32 s51, s51, 1
	s_addk_i32 s51, 0xff00
	s_add_u32 s51, s6, s51
	s_addc_u32 s55, s7, 0
	s_add_i32 s56, 0, 0x10000
	v_add_u32_e32 v152, s56, v137
	ds_read_b128 v[140:143], v152
	ds_read_b128 v[144:147], v152 offset:1024
	ds_read_b128 v[148:151], v152 offset:2048
	ds_read_b128 v[152:155], v152 offset:3072
	s_add_u32 s54, s51, 0x1c0000
	s_addc_u32 s55, s55, 0
	v_lshl_add_u64 v[172:173], s[54:55], 0, v[134:135]
	s_add_i32 m0, s27, 0xc000
	ds_read_b128 v[156:159], v139
	ds_read_b128 v[160:163], v139 offset:1024
	ds_read_b128 v[164:167], v139 offset:2048
	ds_read_b128 v[168:171], v139 offset:3072
	ds_read_b128 v[192:195], v139 offset:4096
	ds_read_b128 v[196:199], v139 offset:5120
	ds_read_b128 v[200:203], v139 offset:6144
	ds_read_b128 v[204:207], v139 offset:7168
	global_load_lds_dwordx4 v[172:173], off
	v_lshl_add_u64 v[172:173], s[54:55], 0, v[132:133]
	s_add_i32 m0, s27, 0xe000
	s_nop 0
	global_load_lds_dwordx4 v[172:173], off
	s_waitcnt lgkmcnt(8)
	s_barrier
	s_waitcnt lgkmcnt(0)
	s_waitcnt lgkmcnt(0)
	v_mfma_f32_16x16x32_bf16 v[126:129], v[140:143], v[156:159], v[126:129]
	v_mfma_f32_16x16x32_bf16 v[122:125], v[148:151], v[156:159], v[122:125]
	v_mfma_f32_16x16x32_bf16 v[118:121], v[140:143], v[164:167], v[118:121]
	v_mfma_f32_16x16x32_bf16 v[114:117], v[148:151], v[164:167], v[114:117]
	v_mfma_f32_16x16x32_bf16 v[102:105], v[140:143], v[192:195], v[102:105]
	v_mfma_f32_16x16x32_bf16 v[98:101], v[148:151], v[192:195], v[98:101]
	v_mfma_f32_16x16x32_bf16 v[86:89], v[140:143], v[200:203], v[86:89]
	v_mfma_f32_16x16x32_bf16 v[82:85], v[148:151], v[200:203], v[82:85]
	v_mfma_f32_16x16x32_bf16 v[126:129], v[144:147], v[160:163], v[126:129]
	v_mfma_f32_16x16x32_bf16 v[122:125], v[152:155], v[160:163], v[122:125]
	v_mfma_f32_16x16x32_bf16 v[118:121], v[144:147], v[168:171], v[118:121]
	v_mfma_f32_16x16x32_bf16 v[114:117], v[152:155], v[168:171], v[114:117]
	v_mfma_f32_16x16x32_bf16 v[102:105], v[144:147], v[196:199], v[102:105]
	v_mfma_f32_16x16x32_bf16 v[98:101], v[152:155], v[196:199], v[98:101]
	v_mfma_f32_16x16x32_bf16 v[86:89], v[144:147], v[204:207], v[86:89]
	v_mfma_f32_16x16x32_bf16 v[82:85], v[152:155], v[204:207], v[82:85]
	s_barrier
	s_add_i32 s51, 0, 0x14000
	v_add_u32_e32 v172, s51, v137
	s_add_i32 s54, s56, s26
	ds_read_b128 v[208:211], v172
	ds_read_b128 v[212:215], v172 offset:1024
	ds_read_b128 v[216:219], v172 offset:2048
	ds_read_b128 v[220:223], v172 offset:3072
	v_lshl_add_u64 v[172:173], s[20:21], 0, v[0:1]
	s_mov_b32 m0, s54
	v_lshl_add_u64 v[224:225], s[20:21], 0, v[130:131]
	global_load_lds_dwordx4 v[172:173], off
	s_add_i32 m0, s54, 0x2000
	s_nop 0
	global_load_lds_dwordx4 v[224:225], off
	s_barrier
	s_waitcnt lgkmcnt(0)
	s_waitcnt lgkmcnt(0)
	v_mfma_f32_16x16x32_bf16 v[110:113], v[208:211], v[156:159], v[110:113]
	v_mfma_f32_16x16x32_bf16 v[106:109], v[216:219], v[156:159], v[106:109]
	v_mfma_f32_16x16x32_bf16 v[94:97], v[208:211], v[164:167], v[94:97]
	v_mfma_f32_16x16x32_bf16 v[90:93], v[216:219], v[164:167], v[90:93]
	v_mfma_f32_16x16x32_bf16 v[78:81], v[208:211], v[192:195], v[78:81]
	v_mfma_f32_16x16x32_bf16 v[74:77], v[216:219], v[192:195], v[74:77]
	v_mfma_f32_16x16x32_bf16 v[70:73], v[208:211], v[200:203], v[70:73]
	v_mfma_f32_16x16x32_bf16 v[66:69], v[216:219], v[200:203], v[66:69]
	v_mfma_f32_16x16x32_bf16 v[110:113], v[212:215], v[160:163], v[110:113]
	v_mfma_f32_16x16x32_bf16 v[106:109], v[220:223], v[160:163], v[106:109]
	v_mfma_f32_16x16x32_bf16 v[94:97], v[212:215], v[168:171], v[94:97]
	v_mfma_f32_16x16x32_bf16 v[90:93], v[220:223], v[168:171], v[90:93]
	v_mfma_f32_16x16x32_bf16 v[78:81], v[212:215], v[196:199], v[78:81]
	v_mfma_f32_16x16x32_bf16 v[74:77], v[220:223], v[196:199], v[74:77]
	v_mfma_f32_16x16x32_bf16 v[70:73], v[212:215], v[204:207], v[70:73]
	v_mfma_f32_16x16x32_bf16 v[66:69], v[220:223], v[204:207], v[66:69]
	s_mov_b32 m0, s27
	v_lshl_add_u64 v[226:227], s[28:29], 0, v[134:135]
	s_barrier
	ds_read_b128 v[156:159], v139 offset:16384
	ds_read_b128 v[160:163], v139 offset:17408
	ds_read_b128 v[164:167], v139 offset:18432
	ds_read_b128 v[168:171], v139 offset:19456
	ds_read_b128 v[192:195], v139 offset:20480
	ds_read_b128 v[196:199], v139 offset:21504
	ds_read_b128 v[200:203], v139 offset:22528
	ds_read_b128 v[204:207], v139 offset:23552
	global_load_lds_dwordx4 v[226:227], off
	v_lshl_add_u64 v[226:227], s[28:29], 0, v[132:133]
	s_mov_b32 m0, s30
	s_nop 0
	global_load_lds_dwordx4 v[226:227], off
	s_barrier
	s_waitcnt lgkmcnt(0)
	s_waitcnt lgkmcnt(0)
	v_mfma_f32_16x16x32_bf16 v[62:65], v[140:143], v[156:159], v[62:65]
	v_mfma_f32_16x16x32_bf16 v[58:61], v[148:151], v[156:159], v[58:61]
	v_mfma_f32_16x16x32_bf16 v[54:57], v[140:143], v[164:167], v[54:57]
	v_mfma_f32_16x16x32_bf16 v[50:53], v[148:151], v[164:167], v[50:53]
	v_mfma_f32_16x16x32_bf16 v[38:41], v[140:143], v[192:195], v[38:41]
	v_mfma_f32_16x16x32_bf16 v[34:37], v[148:151], v[192:195], v[34:37]
	v_mfma_f32_16x16x32_bf16 v[22:25], v[140:143], v[200:203], v[22:25]
	v_mfma_f32_16x16x32_bf16 v[18:21], v[148:151], v[200:203], v[18:21]
	v_mfma_f32_16x16x32_bf16 v[62:65], v[144:147], v[160:163], v[62:65]
	v_mfma_f32_16x16x32_bf16 v[58:61], v[152:155], v[160:163], v[58:61]
	v_mfma_f32_16x16x32_bf16 v[54:57], v[144:147], v[168:171], v[54:57]
	v_mfma_f32_16x16x32_bf16 v[50:53], v[152:155], v[168:171], v[50:53]
	v_mfma_f32_16x16x32_bf16 v[38:41], v[144:147], v[196:199], v[38:41]
	v_mfma_f32_16x16x32_bf16 v[34:37], v[152:155], v[196:199], v[34:37]
	v_mfma_f32_16x16x32_bf16 v[22:25], v[144:147], v[204:207], v[22:25]
	v_mfma_f32_16x16x32_bf16 v[18:21], v[152:155], v[204:207], v[18:21]
	s_barrier
; #define PG8_STAGE(bufoff, gbase, voff) do { _Pragma("unroll") for (int _i = 0; _i < 2; ++_i) \
;         __builtin_amdgcn_global_load_lds((const unsigned*)((const char*)(gbase) + (voff)[_i]), (LAS unsigned*)(lds + (bufoff) + ldsw + _i * 8192), 16, 0, 0); } while (0)
; #define PG8_LDA(dst, b, h) do { _Pragma("unroll") for (int m = 0; m < 4; ++m) _Pragma("unroll") for (int k = 0; k < 2; ++k) dst[m][k] = *(const LAS bf16x8*)(lds + PG8_SA(b, h) + aoff + m * 2048 + k * 1024); } while (0)
; #define PG8_LDB(dst, b, h) do { _Pragma("unroll") for (int n = 0; n < 2; ++n) _Pragma("unroll") for (int k = 0; k < 2; ++k) dst[n][k] = *(const LAS bf16x8*)(lds + PG8_SB(b, h) + boff + n * 2048 + k * 1024); } while (0)
; #define PG8_MMA(ai, bj, At, Bt_) do { __builtin_amdgcn_s_setprio(1); _Pragma("unroll") for (int m = 0; m < 4; ++m) _Pragma("unroll") for (int n = 0; n < 2; ++n) _Pragma("unroll") for (int k = 0; k < 2; ++k) \
;         acc[ai][bj][m][n] = __builtin_amdgcn_mfma_f32_16x16x32_bf16(Bt_[n][k], At[m][k], acc[ai][bj][m][n], 0, 0, 0); __builtin_amdgcn_s_setprio(0); } while (0)
; #define PG8_WAIT_V(n) asm volatile("s_waitcnt vmcnt(" #n ")" ::: "memory")
; #define PG8_WAIT_L(n) asm volatile("s_waitcnt lgkmcnt(" #n ")" ::: "memory")
; #define PG8_BAR __builtin_amdgcn_s_barrier()
; #define PG8_SCHED __builtin_amdgcn_sched_barrier(0)
; template <bool REMAP>
; DI void gemm_phase(LAS unsigned char* lds, const u16* A, int lda, const u16* Bt, int K, u16* O, int ldc, int nunits) {
;     ...
;             PG8_STAGE(PG8_SB(0, 1), b2 + hstepB, voffB);
;             PG8_WAIT_V(6); PG8_BAR; PG8_MMA(1, 1, At, B1); PG8_BAR;
;             PG8_LDB(B0, 1, 0); PG8_SCHED; PG8_LDA(At, 1, 0); PG8_STAGE(PG8_SA(0, 1), a2 + hstepA, voffA);
;             PG8_WAIT_L(8); PG8_BAR; PG8_WAIT_L(0); PG8_MMA(0, 0, At, B0); PG8_BAR; PG8_SCHED;
;             PG8_LDB(B1, 1, 1); PG8_STAGE(PG8_SB(1, 0), b3, voffB);
	s_add_u32 s54, s20, 0x80000
	s_addc_u32 s55, s21, 0
	s_add_i32 s51, s51, s26
	v_lshl_add_u64 v[140:141], s[54:55], 0, v[0:1]
	s_mov_b32 m0, s51
	s_nop 0
	global_load_lds_dwordx4 v[140:141], off
	v_lshl_add_u64 v[140:141], s[54:55], 0, v[130:131]
	s_add_i32 m0, s51, 0x2000
	s_nop 0
	global_load_lds_dwordx4 v[140:141], off
	s_waitcnt vmcnt(6)
	s_barrier
	v_mfma_f32_16x16x32_bf16 v[46:49], v[208:211], v[156:159], v[46:49]
	v_mfma_f32_16x16x32_bf16 v[42:45], v[216:219], v[156:159], v[42:45]
	v_mfma_f32_16x16x32_bf16 v[30:33], v[208:211], v[164:167], v[30:33]
	v_mfma_f32_16x16x32_bf16 v[26:29], v[216:219], v[164:167], v[26:29]
	v_mfma_f32_16x16x32_bf16 v[14:17], v[208:211], v[192:195], v[14:17]
	v_mfma_f32_16x16x32_bf16 v[10:13], v[216:219], v[192:195], v[10:13]
	v_mfma_f32_16x16x32_bf16 v[6:9], v[208:211], v[200:203], v[6:9]
	v_mfma_f32_16x16x32_bf16 v[2:5], v[216:219], v[200:203], v[2:5]
	v_mfma_f32_16x16x32_bf16 v[46:49], v[212:215], v[160:163], v[46:49]
	v_mfma_f32_16x16x32_bf16 v[42:45], v[220:223], v[160:163], v[42:45]
	v_mfma_f32_16x16x32_bf16 v[30:33], v[212:215], v[168:171], v[30:33]
	v_mfma_f32_16x16x32_bf16 v[26:29], v[220:223], v[168:171], v[26:29]
	v_mfma_f32_16x16x32_bf16 v[14:17], v[212:215], v[196:199], v[14:17]
	v_mfma_f32_16x16x32_bf16 v[10:13], v[220:223], v[196:199], v[10:13]
	v_mfma_f32_16x16x32_bf16 v[6:9], v[212:215], v[204:207], v[6:9]
	v_mfma_f32_16x16x32_bf16 v[2:5], v[220:223], v[204:207], v[2:5]
	s_add_i32 s51, 0, 0x18000
	v_add_u32_e32 v152, s51, v137
	s_barrier
	ds_read_b128 v[140:143], v152
	ds_read_b128 v[144:147], v152 offset:1024
	ds_read_b128 v[148:151], v152 offset:2048
	ds_read_b128 v[152:155], v152 offset:3072
	s_add_u32 s28, s28, 0x1c0000
	s_addc_u32 s29, s29, 0
	s_mov_b32 m0, s31
	v_lshl_add_u64 v[208:209], s[28:29], 0, v[134:135]
	ds_read_b128 v[156:159], v139 offset:32768
	ds_read_b128 v[160:163], v139 offset:33792
	ds_read_b128 v[164:167], v139 offset:34816
	ds_read_b128 v[168:171], v139 offset:35840
	ds_read_b128 v[192:195], v139 offset:36864
	ds_read_b128 v[196:199], v139 offset:37888
	ds_read_b128 v[200:203], v139 offset:38912
	ds_read_b128 v[204:207], v139 offset:39936
	global_load_lds_dwordx4 v[208:209], off
	v_lshl_add_u64 v[208:209], s[28:29], 0, v[132:133]
	s_mov_b32 m0, s34
	s_nop 0
	global_load_lds_dwordx4 v[208:209], off
	s_waitcnt lgkmcnt(8)
	s_barrier
	s_waitcnt lgkmcnt(0)
	s_waitcnt lgkmcnt(0)
	v_mfma_f32_16x16x32_bf16 v[126:129], v[140:143], v[156:159], v[126:129]
	v_mfma_f32_16x16x32_bf16 v[122:125], v[148:151], v[156:159], v[122:125]
	v_mfma_f32_16x16x32_bf16 v[118:121], v[140:143], v[164:167], v[118:121]
	v_mfma_f32_16x16x32_bf16 v[114:117], v[148:151], v[164:167], v[114:117]
	v_mfma_f32_16x16x32_bf16 v[102:105], v[140:143], v[192:195], v[102:105]
	v_mfma_f32_16x16x32_bf16 v[98:101], v[148:151], v[192:195], v[98:101]
	v_mfma_f32_16x16x32_bf16 v[86:89], v[140:143], v[200:203], v[86:89]
	v_mfma_f32_16x16x32_bf16 v[82:85], v[148:151], v[200:203], v[82:85]
	v_mfma_f32_16x16x32_bf16 v[126:129], v[144:147], v[160:163], v[126:129]
	v_mfma_f32_16x16x32_bf16 v[122:125], v[152:155], v[160:163], v[122:125]
	v_mfma_f32_16x16x32_bf16 v[118:121], v[144:147], v[168:171], v[118:121]
	v_mfma_f32_16x16x32_bf16 v[114:117], v[152:155], v[168:171], v[114:117]
	v_mfma_f32_16x16x32_bf16 v[102:105], v[144:147], v[196:199], v[102:105]
	v_mfma_f32_16x16x32_bf16 v[98:101], v[152:155], v[196:199], v[98:101]
	v_mfma_f32_16x16x32_bf16 v[86:89], v[144:147], v[204:207], v[86:89]
	v_mfma_f32_16x16x32_bf16 v[82:85], v[152:155], v[204:207], v[82:85]
	s_barrier
	s_add_i32 s28, 0, 0x1c000
	s_add_i32 s29, s51, s26
	v_add_u32_e32 v220, s28, v137
	v_lshl_add_u64 v[172:173], v[172:173], 0, s[18:19]
	s_mov_b32 m0, s29
	ds_read_b128 v[208:211], v220
	ds_read_b128 v[212:215], v220 offset:1024
	ds_read_b128 v[216:219], v220 offset:2048
	ds_read_b128 v[220:223], v220 offset:3072
	global_load_lds_dwordx4 v[172:173], off
	v_lshl_add_u64 v[172:173], v[224:225], 0, s[18:19]
	s_add_i32 m0, s29, 0x2000
	s_nop 0
	global_load_lds_dwordx4 v[172:173], off
	s_barrier
; #define PG8_STAGE(bufoff, gbase, voff) do { _Pragma("unroll") for (int _i = 0; _i < 2; ++_i) \
;         __builtin_amdgcn_global_load_lds((const unsigned*)((const char*)(gbase) + (voff)[_i]), (LAS unsigned*)(lds + (bufoff) + ldsw + _i * 8192), 16, 0, 0); } while (0)
; #define PG8_LDA(dst, b, h) do { _Pragma("unroll") for (int m = 0; m < 4; ++m) _Pragma("unroll") for (int k = 0; k < 2; ++k) dst[m][k] = *(const LAS bf16x8*)(lds + PG8_SA(b, h) + aoff + m * 2048 + k * 1024); } while (0)
; #define PG8_MMA(ai, bj, At, Bt_) do { __builtin_amdgcn_s_setprio(1); _Pragma("unroll") for (int m = 0; m < 4; ++m) _Pragma("unroll") for (int n = 0; n < 2; ++n) _Pragma("unroll") for (int k = 0; k < 2; ++k) \
;         acc[ai][bj][m][n] = __builtin_amdgcn_mfma_f32_16x16x32_bf16(Bt_[n][k], At[m][k], acc[ai][bj][m][n], 0, 0, 0); __builtin_amdgcn_s_setprio(0); } while (0)
; #define PG8_WAIT_V(n) asm volatile("s_waitcnt vmcnt(" #n ")" ::: "memory")
; #define PG8_WAIT_L(n) asm volatile("s_waitcnt lgkmcnt(" #n ")" ::: "memory")
; #define PG8_BAR __builtin_amdgcn_s_barrier()
; #define PG8_SCHED __builtin_amdgcn_sched_barrier(0)
; template <bool REMAP>
; DI void gemm_phase(LAS unsigned char* lds, const u16* A, int lda, const u16* Bt, int K, u16* O, int ldc, int nunits) {
;     ...
;             PG8_BAR; PG8_WAIT_L(0); PG8_MMA(0, 1, At, B1); PG8_BAR;
;             PG8_LDA(At, 1, 1); PG8_STAGE(PG8_SA(1, 0), a3, voffA);
;             PG8_BAR; PG8_WAIT_L(0); PG8_MMA(1, 0, At, B0); PG8_BAR; PG8_SCHED;
;             PG8_STAGE(PG8_SB(1, 1), b3 + hstepB, voffB);
;             PG8_WAIT_V(6); PG8_BAR; PG8_MMA(1, 1, At, B1); PG8_BAR;
	s_waitcnt lgkmcnt(0)
	s_waitcnt lgkmcnt(0)
	v_mfma_f32_16x16x32_bf16 v[110:113], v[208:211], v[156:159], v[110:113]
	v_mfma_f32_16x16x32_bf16 v[106:109], v[216:219], v[156:159], v[106:109]
	v_mfma_f32_16x16x32_bf16 v[94:97], v[208:211], v[164:167], v[94:97]
	v_mfma_f32_16x16x32_bf16 v[90:93], v[216:219], v[164:167], v[90:93]
	v_mfma_f32_16x16x32_bf16 v[78:81], v[208:211], v[192:195], v[78:81]
	v_mfma_f32_16x16x32_bf16 v[74:77], v[216:219], v[192:195], v[74:77]
	v_mfma_f32_16x16x32_bf16 v[70:73], v[208:211], v[200:203], v[70:73]
	v_mfma_f32_16x16x32_bf16 v[66:69], v[216:219], v[200:203], v[66:69]
	v_mfma_f32_16x16x32_bf16 v[110:113], v[212:215], v[160:163], v[110:113]
	v_mfma_f32_16x16x32_bf16 v[106:109], v[220:223], v[160:163], v[106:109]
	v_mfma_f32_16x16x32_bf16 v[94:97], v[212:215], v[168:171], v[94:97]
	v_mfma_f32_16x16x32_bf16 v[90:93], v[220:223], v[168:171], v[90:93]
	v_mfma_f32_16x16x32_bf16 v[78:81], v[212:215], v[196:199], v[78:81]
	v_mfma_f32_16x16x32_bf16 v[74:77], v[220:223], v[196:199], v[74:77]
	v_mfma_f32_16x16x32_bf16 v[70:73], v[212:215], v[204:207], v[70:73]
	v_mfma_f32_16x16x32_bf16 v[66:69], v[220:223], v[204:207], v[66:69]
	s_mov_b32 m0, s35
	v_lshl_add_u64 v[172:173], s[22:23], 0, v[134:135]
	s_barrier
	ds_read_b128 v[156:159], v139 offset:49152
	ds_read_b128 v[160:163], v139 offset:50176
	ds_read_b128 v[164:167], v139 offset:51200
	ds_read_b128 v[168:171], v139 offset:52224
	ds_read_b128 v[192:195], v139 offset:53248
	ds_read_b128 v[196:199], v139 offset:54272
	ds_read_b128 v[200:203], v139 offset:55296
	ds_read_b128 v[204:207], v139 offset:56320
	global_load_lds_dwordx4 v[172:173], off
	v_lshl_add_u64 v[172:173], s[22:23], 0, v[132:133]
	s_mov_b32 m0, s36
	s_nop 0
	global_load_lds_dwordx4 v[172:173], off
	s_barrier
	s_waitcnt lgkmcnt(0)
	s_waitcnt lgkmcnt(0)
	v_mfma_f32_16x16x32_bf16 v[62:65], v[140:143], v[156:159], v[62:65]
	v_mfma_f32_16x16x32_bf16 v[58:61], v[148:151], v[156:159], v[58:61]
	v_mfma_f32_16x16x32_bf16 v[54:57], v[140:143], v[164:167], v[54:57]
	v_mfma_f32_16x16x32_bf16 v[50:53], v[148:151], v[164:167], v[50:53]
	v_mfma_f32_16x16x32_bf16 v[38:41], v[140:143], v[192:195], v[38:41]
	v_mfma_f32_16x16x32_bf16 v[34:37], v[148:151], v[192:195], v[34:37]
	v_mfma_f32_16x16x32_bf16 v[22:25], v[140:143], v[200:203], v[22:25]
	v_mfma_f32_16x16x32_bf16 v[18:21], v[148:151], v[200:203], v[18:21]
	v_mfma_f32_16x16x32_bf16 v[62:65], v[144:147], v[160:163], v[62:65]
	v_mfma_f32_16x16x32_bf16 v[58:61], v[152:155], v[160:163], v[58:61]
	v_mfma_f32_16x16x32_bf16 v[54:57], v[144:147], v[168:171], v[54:57]
	v_mfma_f32_16x16x32_bf16 v[50:53], v[152:155], v[168:171], v[50:53]
	v_mfma_f32_16x16x32_bf16 v[38:41], v[144:147], v[196:199], v[38:41]
	v_mfma_f32_16x16x32_bf16 v[34:37], v[152:155], v[196:199], v[34:37]
	v_mfma_f32_16x16x32_bf16 v[22:25], v[144:147], v[204:207], v[22:25]
	v_mfma_f32_16x16x32_bf16 v[18:21], v[152:155], v[204:207], v[18:21]
	s_barrier
	s_add_u32 s20, s20, 0x80080
	s_addc_u32 s21, s21, 0
	s_add_i32 s22, s28, s26
	v_lshl_add_u64 v[140:141], s[20:21], 0, v[0:1]
	s_mov_b32 m0, s22
	s_nop 0
	global_load_lds_dwordx4 v[140:141], off
	v_lshl_add_u64 v[140:141], s[20:21], 0, v[130:131]
	s_add_i32 m0, s22, 0x2000
	s_nop 0
	global_load_lds_dwordx4 v[140:141], off
	s_waitcnt vmcnt(6)
	s_barrier
	v_mfma_f32_16x16x32_bf16 v[46:49], v[208:211], v[156:159], v[46:49]
	v_mfma_f32_16x16x32_bf16 v[42:45], v[216:219], v[156:159], v[42:45]
	v_mfma_f32_16x16x32_bf16 v[30:33], v[208:211], v[164:167], v[30:33]
	v_mfma_f32_16x16x32_bf16 v[26:29], v[216:219], v[164:167], v[26:29]
	v_mfma_f32_16x16x32_bf16 v[14:17], v[208:211], v[192:195], v[14:17]
	v_mfma_f32_16x16x32_bf16 v[10:13], v[216:219], v[192:195], v[10:13]
	v_mfma_f32_16x16x32_bf16 v[6:9], v[208:211], v[200:203], v[6:9]
	v_mfma_f32_16x16x32_bf16 v[2:5], v[216:219], v[200:203], v[2:5]
	v_mfma_f32_16x16x32_bf16 v[46:49], v[212:215], v[160:163], v[46:49]
	v_mfma_f32_16x16x32_bf16 v[42:45], v[220:223], v[160:163], v[42:45]
	v_mfma_f32_16x16x32_bf16 v[30:33], v[212:215], v[168:171], v[30:33]
	v_mfma_f32_16x16x32_bf16 v[26:29], v[220:223], v[168:171], v[26:29]
	v_mfma_f32_16x16x32_bf16 v[14:17], v[212:215], v[196:199], v[14:17]
	v_mfma_f32_16x16x32_bf16 v[10:13], v[220:223], v[196:199], v[10:13]
	v_mfma_f32_16x16x32_bf16 v[6:9], v[212:215], v[204:207], v[6:9]
	v_mfma_f32_16x16x32_bf16 v[2:5], v[220:223], v[204:207], v[2:5]
	s_add_i32 s20, s50, 2
	s_add_u32 s46, s46, 0x100
	s_addc_u32 s47, s47, 0
	s_addk_i32 s49, 0x80
	s_cmp_gt_u32 s50, 29
	s_mov_b32 s50, s20
	s_barrier
	s_cbranch_scc1 .LBB0_381
